# LRU conv taps in LDS re-laid out so each 16-lane group reads 256 contiguous bytes (removes a two-way bank conflict on 10 ds_read_b128 per super-chunk)
# speedup vs baseline: 1.0012x; 1.0012x over previous
; #define LAS __attribute__((address_space(3)))
; __device__ __forceinline__ int opaque_tid() { int t = threadIdx.x; asm volatile("" : "+v"(t)); return t; }
; #define LDS_BARRIER() do { asm volatile("s_waitcnt lgkmcnt(0)" ::: "memory"); __builtin_amdgcn_s_barrier(); asm volatile("" ::: "memory"); } while (0)
; template <int dir>
; __device__ __forceinline__ void lru_pass(LAS unsigned char* lds, const Params& P, int b, int h, int q, bool dry) {
;     ...
;     const int cgp = tid & 15, tr = tid >> 4;
;     const int s_i = 16 * ((nl >> 2) & 1) + ((nl >> 3) << 2) + (nl & 3);
;     const bf16_t* Zg = Z + ZSLAB(8 + h, (size_t)b * SEQ) + q * 32;
;     unsigned* Hg = HFW + (size_t)b * SEQ * DM + h * 128 + q * 32;
;     {
; #pragma unroll
;         for (int i = 0; i < 2; ++i) { const int idx = tid + i * NTHREADS, gate = idx >> 9, n = (idx >> 4) & 31, kc = idx & 15;
;             *(LAS u32x4*)(WB + (gate * 32 + n) * XC_PITCH + kc * 16) = *(const u32x4*)(LruW + ((size_t)((dir * 2 + gate) * 8 + h) * 128 + q * 32 + n) * 128 + kc * 8); }
;         const float br = -LOG2E * P.lru_ba[(dir * 8 + h) * 128 + chl], bi = -LOG2E * P.lru_bx[(dir * 8 + h) * 128 + chl];
;         const float lam = P.lru_lambda[dir * 1024 + ch];
;         const float cl = -8.0f * LOG2E * log1pf(__expf(-lam));
;         float carry = 0.f;
;         LruTile cur = lru_tile(Z, ZC, b, h, dir, 0);
;         u32x4 rows[11];
;         constexpr int NIN = dir == 0 ? 2 : 4;
;         u32x4 inr[NIN];
;         lru_load_rows(rows, cur, tr, cgp);
; __device__ __forceinline__ void lru_strip(LAS unsigned char* lds, const Params& P, int strip, bool dry) {
;     const int tid = opaque_tid();
;     const int b = strip >> 5, h = (strip >> 2) & 7, q = strip & 3;
;     LAS float* CWL = (LAS float*)(lds + 256 * XC_PITCH + 2048 + 64 * XC_PITCH);
;     for (int i = tid; i < 640; i += NTHREADS) { const int k = i >> 7, c = i & 127; CWL[i] = k < 4 ? P.conv_w[k * 1024 + h * 128 + c] : P.conv_b[h * 128 + c]; }
;     LDS_BARRIER();
;     lru_pass<0>(lds, P, b, h, q, dry);
.LBB0_278:
	s_ashr_i32 s25, s2, 3
	v_mov_b32_e32 v128, v167
	s_bfe_u32 s26, s25, 0x30002
	s_lshl_b32 s27, s26, 7
	v_and_b32_e32 v204, 0x7f, v128
	v_or_b32_e32 v204, s27, v204
	v_lshrrev_b32_e32 v205, 7, v128
	v_lshl_or_b32 v205, v205, 10, v204
	v_lshlrev_b32_e32 v205, 2, v205
	v_lshlrev_b32_e32 v204, 2, v204
	global_load_dword v205, v205, s[52:53]
	global_load_dword v204, v204, s[54:55]
	v_readlane_b32 s0, v255, 19
	s_nop 3
	v_lshrrev_b32_e32 v206, 7, v128
	v_lshl_add_u32 v206, v206, 9, s0
	v_bfe_u32 v207, v128, 2, 1
	v_lshl_add_u32 v206, v207, 8, v206
	v_bfe_u32 v207, v128, 3, 4
	v_lshl_add_u32 v206, v207, 4, v206
	v_and_b32_e32 v207, 3, v128
	v_lshl_add_u32 v206, v207, 2, v206
	v_mov_b32_e32 v12, v167
	s_lshl_b32 s0, s25, 5
	s_and_b32 s28, s0, 0x60
	v_and_b32_e32 v15, 31, v12
	v_or_b32_e32 v17, s28, v15
	v_add_u32_e32 v14, 0x200, v12
	v_or_b32_e32 v11, s27, v17
	v_ashrrev_i32_e32 v8, 9, v12
	v_ashrrev_i32_e32 v10, 9, v14
	v_lshlrev_b32_e32 v16, 2, v11
	v_and_b32_e32 v13, 15, v12
	v_lshl_or_b32 v2, v8, 3, s26
	v_lshl_or_b32 v6, v10, 3, s26
	global_load_dword v18, v16, s[64:65]
	v_bfe_u32 v9, v12, 4, 5
	v_lshlrev_b32_e32 v64, 4, v13
	v_ashrrev_i32_e32 v3, 31, v2
	v_ashrrev_i32_e32 v7, 31, v6
	v_or_b32_e32 v4, s28, v9
	v_lshl_add_u64 v[0:1], s[38:39], 0, v[64:65]
	v_lshlrev_b64 v[2:3], 15, v[2:3]
	v_lshlrev_b64 v[6:7], 15, v[6:7]
	v_lshlrev_b32_e32 v4, 8, v4
	v_mov_b32_e32 v5, v65
	v_lshl_add_u64 v[2:3], v[0:1], 0, v[2:3]
	v_lshl_add_u64 v[0:1], v[0:1], 0, v[6:7]
	v_lshl_add_u64 v[2:3], v[2:3], 0, v[4:5]
	v_lshl_add_u64 v[4:5], v[0:1], 0, v[4:5]
	global_load_dwordx4 v[0:3], v[2:3], off
	s_nop 0
	global_load_dwordx4 v[4:7], v[4:5], off
	v_lshlrev_b32_e32 v11, 2, v12
	v_lshl_or_b32 v21, v8, 5, v9
	v_add_u32_e32 v8, s88, v64
	v_lshl_or_b32 v9, v10, 5, v9
	v_and_b32_e32 v22, 16, v11
	v_mad_u64_u32 v[10:11], s[4:5], v21, s89, v[8:9]
	v_mad_u64_u32 v[8:9], s[4:5], v9, s89, v[8:9]
	global_load_dword v9, v16, s[58:59]
	global_load_dword v11, v16, s[62:63]
	s_lshl_b32 s0, s2, 5
	s_and_b32 s0, s0, 0xe0
	s_or_b32 s1, s0, s25
	s_ashr_i32 s78, s1, 5
	s_ashr_i32 s79, s78, 31
	s_lshl_b32 s20, s26, 22
	s_lshl_b64 s[18:19], s[78:79], 19
	s_lshl_b64 s[44:45], s[78:79], 23
	v_readlane_b32 s1, v255, 18
	s_add_u32 s1, s1, s44
	s_addc_u32 s4, s33, s45
	s_lshl_b32 s5, s27, 2
	s_add_u32 s1, s1, s5
	s_addc_u32 s4, s4, 0
	s_add_u32 s5, s68, s18
	s_addc_u32 s6, s69, s19
	s_lshl_b32 s7, s27, 1
	s_add_u32 s48, s5, s7
	s_addc_u32 s49, s6, 0
	s_add_u32 s50, s48, 0x1000
	s_addc_u32 s51, s49, 0
	s_add_u32 s56, s48, 0x1800
	s_addc_u32 s57, s49, 0
	s_add_u32 s60, s48, 0x2000
	s_addc_u32 s61, s49, 0
	s_add_u32 s66, s48, 0x2800
	s_addc_u32 s67, s49, 0
	s_add_u32 s70, s48, 0x3000
	s_addc_u32 s71, s49, 0
	v_ashrrev_i32_e32 v36, 4, v12
	v_lshlrev_b32_e32 v37, 3, v13
	s_add_u32 s72, s48, 0x3800
	s_addc_u32 s73, s49, 0
	s_add_u32 s74, s48, 0x4000
	s_addc_u32 s75, s49, 0
	s_add_u32 s76, s48, 0x4800
	s_addc_u32 s77, s49, 0
	v_readfirstlane_b32 s0, v12
	s_ashr_i32 s6, s0, 6
	s_lshl_b32 s5, s28, 2
	s_add_u32 s8, s1, s5
	v_bfe_u32 v19, v12, 5, 1
	v_lshrrev_b32_e32 v20, 1, v12
	v_and_b32_e32 v33, 3, v12
	s_addc_u32 s9, s4, 0
	v_lshl_or_b32 v110, v36, 13, v37
	v_mov_b32_e32 v111, v65
	v_lshlrev_b64 v[110:111], 1, v[110:111]
	v_lshl_add_u64 v[108:109], s[48:49], 0, v[110:111]
	global_load_dwordx4 v[68:71], v[108:109], off offset:-2048
	global_load_dwordx4 v[72:75], v[108:109], off
	global_load_dwordx4 v[76:79], v[108:109], off offset:2048
	v_lshl_add_u64 v[108:109], s[50:51], 0, v[110:111]
	global_load_dwordx4 v[80:83], v[108:109], off
	v_lshl_add_u64 v[108:109], s[56:57], 0, v[110:111]
	global_load_dwordx4 v[84:87], v[108:109], off
	v_lshl_add_u64 v[108:109], s[60:61], 0, v[110:111]
	global_load_dwordx4 v[88:91], v[108:109], off
	v_lshl_add_u64 v[108:109], s[66:67], 0, v[110:111]
	global_load_dwordx4 v[92:95], v[108:109], off
	v_lshl_add_u64 v[108:109], s[70:71], 0, v[110:111]
	global_load_dwordx4 v[96:99], v[108:109], off
	v_lshl_add_u64 v[108:109], s[72:73], 0, v[110:111]
	global_load_dwordx4 v[100:103], v[108:109], off
	v_lshl_add_u64 v[108:109], s[74:75], 0, v[110:111]
	global_load_dwordx4 v[104:107], v[108:109], off
	v_lshl_add_u64 v[108:109], s[76:77], 0, v[110:111]
	global_load_dwordx4 v[108:111], v[108:109], off
	s_waitcnt vmcnt(14)
	ds_write_b128 v10, v[0:3]
	s_waitcnt vmcnt(13)
; #define LAS __attribute__((address_space(3)))
; template <int dir>
; __device__ __forceinline__ void lru_pass(LAS unsigned char* lds, const Params& P, int b, int h, int q, bool dry) {
;     ...
;     {
; #pragma unroll
;         for (int i = 0; i < 2; ++i) { const int idx = tid + i * NTHREADS, gate = idx >> 9, n = (idx >> 4) & 31, kc = idx & 15;
;             *(LAS u32x4*)(WB + (gate * 32 + n) * XC_PITCH + kc * 16) = *(const u32x4*)(LruW + ((size_t)((dir * 2 + gate) * 8 + h) * 128 + q * 32 + n) * 128 + kc * 8); }
;         const float br = -LOG2E * P.lru_ba[(dir * 8 + h) * 128 + chl], bi = -LOG2E * P.lru_bx[(dir * 8 + h) * 128 + chl];
;         const float lam = P.lru_lambda[dir * 1024 + ch];
;         const float cl = -8.0f * LOG2E * log1pf(__expf(-lam));
;         float carry = 0.f;
;         LruTile cur = lru_tile(Z, ZC, b, h, dir, 0);
;         u32x4 rows[11];
;         constexpr int NIN = dir == 0 ? 2 : 4;
;         u32x4 inr[NIN];
;         lru_load_rows(rows, cur, tr, cgp);
; #pragma unroll
;         for (int i = 0; i < NIN; ++i) inr[i] = (u32x4){0u, 0u, 0u, 0u};
;         int t0_prev = 0;
;         for (int sc = 0; sc < 9; ++sc) {
;             const bool isctx = (sc == 0);
;             const int t0 = cur.t0;
; #pragma unroll
;             for (int j = 0; j < 11; ++j) { if (j != 0 && j < 9) continue;
;                 const int t = t0 + tr * 8 - 1 + j; if (t < 0 || t >= cur.L) rows[j] = (u32x4){0u, 0u, 0u, 0u}; }
;             f32x2 cw2[4][4], cb2[4];
; #pragma unroll
;             for (int k = 0; k < 5; ++k) { const f32x4 a = *(const LAS f32x4*)(CWL + k * 128 + cgp * 8), c2 = *(const LAS f32x4*)(CWL + k * 128 + cgp * 8 + 4);
	ds_write_b128 v8, v[4:7]
	ds_write_b32 v206, v205
	v_cmp_gt_u32_e32 vcc, 0x80, v128
	s_and_saveexec_b64 s[14:15], vcc
	ds_write_b32 v206, v204 offset:2048
	s_or_b64 exec, exec, s[14:15]
	v_mul_f32_e32 v16, 0xbfb8aa3b, v18
	v_exp_f32_e32 v16, v16
	s_lshl_b32 s1, s6, 5
	s_and_b32 s0, s0, 0x3fffffc0
	v_add_u32_e32 v39, 0, v64
	v_add_f32_e32 v2, 1.0, v16
	v_add_f32_e32 v3, -1.0, v2
	v_frexp_mant_f32_e32 v4, v2
	v_cvt_f64_f32_e32 v[0:1], v2
	v_sub_f32_e32 v5, v3, v2
	v_frexp_exp_i32_f64_e32 v0, v[0:1]
	v_cmp_gt_f32_e32 vcc, s80, v4
	v_sub_f32_e32 v3, v16, v3
	v_add_f32_e32 v1, 1.0, v5
	v_subbrev_co_u32_e32 v0, vcc, 0, v0, vcc
	v_add_f32_e32 v1, v3, v1
	v_sub_u32_e32 v3, 0, v0
	v_ldexp_f32 v2, v2, v3
	v_ldexp_f32 v1, v1, v3
	v_add_f32_e32 v3, -1.0, v2
	v_add_f32_e32 v4, 1.0, v2
	v_add_f32_e32 v5, 1.0, v3
	v_add_f32_e32 v6, -1.0, v4
	v_sub_f32_e32 v5, v2, v5
	v_sub_f32_e32 v2, v2, v6
	v_add_f32_e32 v5, v1, v5
	v_add_f32_e32 v1, v1, v2
	v_add_f32_e32 v6, v4, v1
	v_rcp_f32_e32 v7, v6
	v_add_f32_e32 v2, v3, v5
	v_sub_f32_e32 v4, v6, v4
	v_sub_f32_e32 v3, v2, v3
	v_sub_f32_e32 v1, v1, v4
	v_mul_f32_e32 v4, v2, v7
	v_sub_f32_e32 v3, v5, v3
	v_mul_f32_e32 v5, v6, v4
	v_fma_f32 v8, v4, v6, -v5
	v_fmac_f32_e32 v8, v4, v1
	v_add_f32_e32 v10, v5, v8
	v_sub_f32_e32 v18, v2, v10
	v_sub_f32_e32 v2, v2, v18
	v_sub_f32_e32 v5, v10, v5
	v_sub_f32_e32 v2, v2, v10
	v_sub_f32_e32 v5, v5, v8
	v_add_f32_e32 v2, v3, v2
	v_add_f32_e32 v2, v5, v2
	v_add_f32_e32 v3, v18, v2
	v_mul_f32_e32 v5, v7, v3
	v_mul_f32_e32 v10, v6, v5
	v_fma_f32 v6, v5, v6, -v10
	v_fmac_f32_e32 v6, v5, v1
	v_add_f32_e32 v1, v10, v6
	v_sub_f32_e32 v8, v18, v3
	v_sub_f32_e32 v18, v3, v1
	v_sub_f32_e32 v3, v3, v18
	v_add_f32_e32 v2, v2, v8
	v_sub_f32_e32 v10, v1, v10
	v_sub_f32_e32 v1, v3, v1
	v_sub_f32_e32 v6, v10, v6
	v_add_f32_e32 v1, v2, v1
	v_cvt_f32_i32_e32 v0, v0
	v_add_f32_e32 v8, v4, v5
	v_add_f32_e32 v1, v6, v1
	v_add_f32_e32 v1, v18, v1
	v_sub_f32_e32 v2, v8, v4
	v_mul_f32_e32 v1, v7, v1
	v_sub_f32_e32 v2, v5, v2
	v_add_f32_e32 v1, v2, v1
	v_mul_f32_e32 v5, 0x3f317218, v0
	v_add_f32_e32 v2, v8, v1
	v_fma_f32 v6, v0, s81, -v5
	v_fmac_f32_e32 v6, 0xb102e308, v0
	v_sub_f32_e32 v0, v2, v8
	v_mul_f32_e32 v3, v2, v2
	v_sub_f32_e32 v0, v1, v0
	v_add_f32_e32 v1, v5, v6
	v_fmamk_f32 v4, v3, 0x3e9b6dac, v200
	v_sub_f32_e32 v5, v1, v5
	v_fmaak_f32 v4, v3, v4, 0x3f2aaada
	v_sub_f32_e32 v5, v6, v5
	v_ldexp_f32 v6, v2, 1
	v_mul_f32_e32 v2, v2, v3
	v_mul_f32_e32 v2, v2, v4
	v_add_f32_e32 v3, v6, v2
	v_sub_f32_e32 v4, v3, v6
	v_ldexp_f32 v0, v0, 1
	v_sub_f32_e32 v2, v2, v4
	v_add_f32_e32 v0, v0, v2
	v_add_f32_e32 v2, v3, v0
	v_sub_f32_e32 v3, v2, v3
	v_sub_f32_e32 v0, v0, v3
	v_add_f32_e32 v3, v1, v2
	v_sub_f32_e32 v4, v3, v1
	v_sub_f32_e32 v6, v3, v4
	v_sub_f32_e32 v1, v1, v6
	v_sub_f32_e32 v2, v2, v4
	v_add_f32_e32 v1, v2, v1
	v_add_f32_e32 v2, v5, v0
	v_sub_f32_e32 v4, v2, v5
	v_add_f32_e32 v1, v2, v1
	v_sub_f32_e32 v6, v2, v4
	v_add_f32_e32 v2, v3, v1
	v_sub_f32_e32 v5, v5, v6
	v_sub_f32_e32 v0, v0, v4
	v_sub_f32_e32 v3, v2, v3
	v_add_f32_e32 v0, v0, v5
	v_sub_f32_e32 v1, v1, v3
	v_add_f32_e32 v0, v0, v1
	v_add_f32_e32 v0, v2, v0
	v_cmp_neq_f32_e32 vcc, s91, v16
	v_mov_b32_e32 v1, v65
	v_lshlrev_b32_e32 v41, 4, v19
	v_cndmask_b32_e32 v0, v201, v0, vcc
	v_cmp_ngt_f32_e32 vcc, -1.0, v16
	s_cmp_eq_u32 s6, 7
	v_or_b32_e32 v35, s1, v41
	v_cndmask_b32_e32 v0, v202, v0, vcc
	v_cmp_neq_f32_e32 vcc, -1.0, v16
	v_ashrrev_i32_e32 v32, 2, v12
	v_ashrrev_i32_e32 v34, 2, v14
	v_cndmask_b32_e32 v0, v203, v0, vcc
	v_cmp_lt_f32_e64 vcc, |v16|, s92
	v_lshlrev_b32_e32 v53, 4, v33
	v_mul_lo_u32 v48, v32, s87
	v_cndmask_b32_e32 v6, v0, v16, vcc
	v_lshlrev_b32_e32 v1, 2, v15
	v_lshlrev_b32_e32 v2, 4, v12
	v_add_u32_e32 v140, s94, v1
	v_and_b32_e32 v3, 48, v2
	v_and_b32_e32 v64, 0x70, v2
	v_and_or_b32 v2, v20, 12, v33
	v_or3_b32 v2, v2, v22, s1
	v_lshl_add_u32 v147, s0, 2, v140
	s_cselect_b64 s[0:1], -1, 0
	s_cmp_eq_u32 s6, 6
	s_cselect_b64 s[16:17], -1, 0
	s_cmp_eq_u32 s6, 5
	s_cselect_b64 s[4:5], -1, 0
	s_cmp_eq_u32 s6, 4
	v_lshl_add_u64 v[130:131], s[8:9], 0, v[64:65]
	s_cselect_b64 s[8:9], -1, 0
	s_cmp_eq_u32 s6, 3
	s_cselect_b64 s[10:11], -1, 0
	s_cmp_eq_u32 s6, 2
	s_cselect_b64 s[12:13], -1, 0
	s_cmp_eq_u32 s6, 1
	s_cselect_b64 s[14:15], -1, 0
	s_add_u32 s46, s20, s18
	s_addc_u32 s47, 0, s19
	s_lshl_b32 s6, s2, 3
	v_ashrrev_i32_e32 v33, 31, v32
	v_mul_lo_u32 v50, v35, s89
	v_mul_lo_u32 v51, v35, s87
	v_mul_lo_u32 v52, v35, s30
	v_ashrrev_i32_e32 v35, 31, v34
	s_bfe_u32 s29, s2, 0x20003
	s_and_b32 s6, s6, 0xc0
	v_lshlrev_b64 v[32:33], 8, v[32:33]
	v_mul_lo_u32 v2, v2, s89
	v_add_u32_e32 v46, s96, v1
	v_mul_lo_u32 v49, v34, s87
	v_add_u32_e32 v1, 0x400, v12
	v_lshlrev_b64 v[34:35], 8, v[34:35]
	v_lshl_add_u64 v[32:33], s[46:47], 0, v[32:33]
	s_add_u32 s18, s82, s46
	v_lshlrev_b32_e32 v38, 4, v13
	v_add_u32_e32 v129, s96, v64
	v_add_u32_e32 v42, 0, v2
	v_mov_b32_e32 v2, s88
	v_ashrrev_i32_e32 v143, 3, v1
	v_add_u32_e32 v1, 0x600, v12
	v_lshl_add_u64 v[34:35], s[46:47], 0, v[34:35]
	v_or3_b32 v32, v32, s6, v53
	v_lshl_or_b32 v64, v36, 10, v37
	s_addc_u32 s19, s83, s47
	v_mov_b32_e32 v66, v65
	v_mov_b32_e32 v67, v65
	s_waitcnt vmcnt(12)
	v_mul_f32_e32 v0, 0xbfb8aa3b, v9
	s_waitcnt vmcnt(11)
; #define LAS __attribute__((address_space(3)))
; __device__ __forceinline__ float bf_lo(unsigned u) { return __uint_as_float(u << 16); }
; __device__ __forceinline__ float bf_hi(unsigned u) { return __uint_as_float(u & 0xffff0000u); }
; template <int dir>
; __device__ __forceinline__ void lru_pass(LAS unsigned char* lds, const Params& P, int b, int h, int q, bool dry) {
;     ...
;         for (int sc = 0; sc < 9; ++sc) {
;             const bool isctx = (sc == 0);
;             const int t0 = cur.t0;
; #pragma unroll
;             for (int j = 0; j < 11; ++j) { if (j != 0 && j < 9) continue;
;                 const int t = t0 + tr * 8 - 1 + j; if (t < 0 || t >= cur.L) rows[j] = (u32x4){0u, 0u, 0u, 0u}; }
;             f32x2 cw2[4][4], cb2[4];
; #pragma unroll
;             for (int k = 0; k < 5; ++k) { const f32x4 a = *(const LAS f32x4*)(CWL + k * 128 + cgp * 8), c2 = *(const LAS f32x4*)(CWL + k * 128 + cgp * 8 + 4);
;                 if (k < 4) { cw2[k][0] = (f32x2){a[0], a[1]}; cw2[k][1] = (f32x2){a[2], a[3]}; cw2[k][2] = (f32x2){c2[0], c2[1]}; cw2[k][3] = (f32x2){c2[2], c2[3]}; }
;                 else { cb2[0] = (f32x2){a[0], a[1]}; cb2[1] = (f32x2){a[2], a[3]}; cb2[2] = (f32x2){c2[0], c2[1]}; cb2[3] = (f32x2){c2[2], c2[3]}; } }
; #pragma unroll
;             for (int j = 0; j < 8; ++j) {
;                 f32x2 o0 = cb2[0], o1 = cb2[1], o2 = cb2[2], o3 = cb2[3];
; #pragma unroll
;                 for (int k = 0; k < 4; ++k) { const u32x4 rr = rows[j + k];
;                     o0 = cw2[k][0] * (f32x2){bf_lo(rr.x), bf_hi(rr.x)} + o0; o1 = cw2[k][1] * (f32x2){bf_lo(rr.y), bf_hi(rr.y)} + o1;
;                     o2 = cw2[k][2] * (f32x2){bf_lo(rr.z), bf_hi(rr.z)} + o2; o3 = cw2[k][3] * (f32x2){bf_lo(rr.w), bf_hi(rr.w)} + o3; }
	v_mul_f32_e32 v16, 0xbfb8aa3b, v11
	v_add_u32_e32 v40, s95, v3
	v_mad_u32_u24 v43, v15, s89, v2
	v_lshl_add_u32 v44, v17, 1, 0
	v_lshl_add_u32 v45, v15, 1, s95
	v_mul_lo_u32 v47, v36, s93
	v_ashrrev_i32_e32 v148, 3, v12
	v_ashrrev_i32_e32 v145, 3, v14
	v_ashrrev_i32_e32 v141, 3, v1
	v_or3_b32 v34, v34, s6, v53
	v_lshl_add_u64 v[134:135], s[40:41], 0, v[32:33]
	v_lshl_add_u64 v[136:137], v[64:65], 1, s[18:19]
	v_mov_b32_e32 v64, v65
	v_add_u32_e32 v32, 0, v38
	v_mov_b64_e32 v[114:115], v[66:67]
	v_mov_b64_e32 v[118:119], v[66:67]
	s_mov_b32 s90, 0
	v_mul_f32_e32 v138, 0xc138aa3b, v6
	v_lshl_add_u32 v139, v36, 3, -1
	v_cmp_eq_u32_e32 vcc, 0, v19
	v_mul_lo_u32 v149, v148, s30
	v_mul_lo_u32 v146, v145, s30
	v_mul_lo_u32 v144, v143, s30
	v_mul_lo_u32 v142, v141, s30
	v_mov_b32_e32 v1, v0
	v_mov_b32_e32 v2, v0
	v_mov_b32_e32 v3, v0
	v_mov_b32_e32 v4, v0
	v_mov_b32_e32 v5, v0
	v_mov_b32_e32 v6, v0
	v_mov_b32_e32 v7, v0
	v_mov_b32_e32 v8, v0
	v_mov_b32_e32 v9, v0
	v_mov_b32_e32 v10, v0
	v_mov_b32_e32 v11, v0
	v_mov_b32_e32 v12, v0
	v_mov_b32_e32 v13, v0
	v_mov_b32_e32 v14, v0
	v_mov_b32_e32 v15, v0
	v_mov_b32_e32 v17, v16
	v_mov_b32_e32 v18, v16
	v_mov_b32_e32 v19, v16
	v_mov_b32_e32 v20, v16
	v_mov_b32_e32 v21, v16
	v_mov_b32_e32 v22, v16
	v_mov_b32_e32 v23, v16
	v_mov_b32_e32 v24, v16
	v_mov_b32_e32 v25, v16
	v_mov_b32_e32 v26, v16
	v_mov_b32_e32 v27, v16
	v_mov_b32_e32 v28, v16
	v_mov_b32_e32 v29, v16
	v_mov_b32_e32 v30, v16
	v_mov_b32_e32 v31, v16
	v_lshl_add_u64 v[132:133], s[40:41], 0, v[34:35]
	s_movk_i32 s92, 0x100
	v_mov_b32_e32 v165, 0
	s_mov_b64 s[80:81], 0
	v_add_u32_e32 v150, 0x15c00, v32
	v_add_u32_e32 v151, v39, v47
	v_add_u32_e32 v158, v40, v48
	v_add_u32_e32 v159, v40, v49
	v_add_u32_e32 v160, v42, v41
	v_add_u32_e32 v161, v43, v41
	v_add_u32_e32 v162, v44, v50
	v_add_u32_e32 v163, v45, v51
	v_add_u32_e32 v164, v46, v52
	v_mov_b64_e32 v[112:113], v[64:65]
	v_mov_b64_e32 v[116:117], v[64:65]
	s_mov_b32 s91, 0
	s_mov_b32 s93, 0
	s_mov_b32 s97, 0
	v_lshrrev_b32_e32 v254, 8, v167
	v_mul_u32_u24_e32 v252, 0x1400, v254
	v_add_u32_e32 v158, v158, v252
	v_add_u32_e32 v159, v159, v252
	v_add_u32_e32 v159, 0xffffec00, v159
	v_lshlrev_b32_e32 v252, 14, v254
	v_mov_b32_e32 v253, 0
	v_lshl_add_u64 v[134:135], v[252:253], 0, v[134:135]
	v_lshl_add_u64 v[132:133], v[252:253], 0, v[132:133]
	s_mov_b32 s18, 0xffffc000
	s_mov_b32 s19, -1
	v_lshl_add_u64 v[132:133], v[132:133], 0, s[18:19]
	v_mul_u32_u24_e32 v252, 0x3600, v254
	v_add_u32_e32 v149, v149, v252
	v_add_u32_e32 v146, v146, v252
	v_add_u32_e32 v144, v144, v252
	v_add_u32_e32 v142, v142, v252
	v_add_u32_e32 v146, 0xffffee00, v146
	v_add_u32_e32 v144, 0xffffdc00, v144
	v_add_u32_e32 v142, 0xffffca00, v142
	v_mul_u32_u24_e32 v252, 0x60, v254
	v_add_u32_e32 v148, v148, v252
	v_add_u32_e32 v145, v145, v252
	v_add_u32_e32 v143, v143, v252
	v_add_u32_e32 v141, v141, v252
	v_add_u32_e32 v145, 0xffffffe0, v145
	v_add_u32_e32 v143, 0xffffffc0, v143
	v_add_u32_e32 v141, 0xffffffa0, v141
	v_lshrrev_b32_e32 v253, 6, v167
	s_nop 1
	v_readfirstlane_b32 s18, v253
	s_lshr_b32 s101, s18, 2
	s_or_b32 s19, s18, 4
	s_cmp_eq_u32 s19, 7
	s_cselect_b64 s[0:1], -1, 0
	s_cmp_eq_u32 s19, 6
	s_cselect_b64 s[16:17], -1, 0
	s_cmp_eq_u32 s19, 5
	s_cselect_b64 s[4:5], -1, 0
	s_cmp_eq_u32 s19, 4
	s_cselect_b64 s[8:9], -1, 0
	s_mov_b64 s[10:11], 0
	s_mov_b64 s[12:13], 0
	s_mov_b64 s[14:15], 0
	s_mov_b32 s98, 0
	s_cmp_eq_u32 s101, 0
	s_cselect_b32 s99, 0x14400, 0
	s_cselect_b32 s100, 0, 0x400
	v_add_u32_e32 v253, 0x14000, v147
	v_mov_b32_e32 v254, 1.0
	v_mov_b32_e32 v252, 0
	ds_write2_b32 v253, v254, v252 offset1:32
	s_waitcnt lgkmcnt(0)
	s_barrier
	s_cmp_eq_u32 s101, 0
	s_cbranch_scc1 .Lpp_f_nox
	s_barrier
.Lpp_f_nox:
.LBB0_292:
	v_add_u32_e32 v32, s97, v139
	v_cmp_lt_i32_e64 s[18:19], -1, v32
	v_cmp_gt_i32_e64 s[20:21], s92, v32
	s_and_b64 s[18:19], s[18:19], s[20:21]
	v_add_u32_e32 v33, 9, v32
	s_waitcnt vmcnt(10)
	v_cndmask_b32_e64 v71, 0, v71, s[18:19]
	v_cndmask_b32_e64 v70, 0, v70, s[18:19]
	v_cndmask_b32_e64 v69, 0, v69, s[18:19]
	v_cndmask_b32_e64 v68, 0, v68, s[18:19]
	v_cmp_lt_i32_e64 s[18:19], -10, v32
	v_cmp_gt_i32_e64 s[20:21], s92, v33
	s_and_b64 s[18:19], s[18:19], s[20:21]
	v_add_u32_e32 v33, 10, v32
	s_waitcnt vmcnt(1)
	v_cndmask_b32_e64 v107, 0, v107, s[18:19]
	v_cndmask_b32_e64 v106, 0, v106, s[18:19]
	v_cndmask_b32_e64 v105, 0, v105, s[18:19]
	v_cndmask_b32_e64 v104, 0, v104, s[18:19]
	v_cmp_lt_i32_e64 s[18:19], -11, v32
	v_cmp_gt_i32_e64 s[20:21], s92, v33
	ds_read_b128 v[60:63], v150
	ds_read_b128 v[52:55], v150 offset:256
	ds_read_b128 v[44:47], v150 offset:768
	ds_read_b128 v[56:59], v150 offset:512
	ds_read_b128 v[40:43], v150 offset:1280
	ds_read_b128 v[48:51], v150 offset:1024
	ds_read_b128 v[120:123], v150 offset:2304
	ds_read_b128 v[124:127], v150 offset:2048
	ds_read_b128 v[32:35], v150 offset:1792
	ds_read_b128 v[36:39], v150 offset:1536
	v_lshlrev_b32_e32 v66, 16, v68
	v_and_b32_e32 v67, 0xffff0000, v68
	v_lshlrev_b32_e32 v154, 16, v69
	v_and_b32_e32 v155, 0xffff0000, v69
	v_lshlrev_b32_e32 v168, 16, v70
	v_and_b32_e32 v169, 0xffff0000, v70
	s_waitcnt lgkmcnt(2)
; #define LAS __attribute__((address_space(3)))
; __device__ __forceinline__ unsigned cvt_pk_bf16(float lo, float hi) { unsigned r; asm volatile("v_cvt_pk_bf16_f32 %0, %1, %2" : "=v"(r) : "v"(lo), "v"(hi)); return r; }
; __device__ __forceinline__ float bf_lo(unsigned u) { return __uint_as_float(u << 16); }
; __device__ __forceinline__ float bf_hi(unsigned u) { return __uint_as_float(u & 0xffff0000u); }
; template <int dir>
; __device__ __forceinline__ void lru_pass(LAS unsigned char* lds, const Params& P, int b, int h, int q, bool dry) {
;     ...
;             for (int j = 0; j < 8; ++j) {
;                 f32x2 o0 = cb2[0], o1 = cb2[1], o2 = cb2[2], o3 = cb2[3];
; #pragma unroll
;                 for (int k = 0; k < 4; ++k) { const u32x4 rr = rows[j + k];
;                     o0 = cw2[k][0] * (f32x2){bf_lo(rr.x), bf_hi(rr.x)} + o0; o1 = cw2[k][1] * (f32x2){bf_lo(rr.y), bf_hi(rr.y)} + o1;
;                     o2 = cw2[k][2] * (f32x2){bf_lo(rr.z), bf_hi(rr.z)} + o2; o3 = cw2[k][3] * (f32x2){bf_lo(rr.w), bf_hi(rr.w)} + o3; }
;                 u32x4 w; w.x = cvt_pk_bf16(o0[0], o0[1]); w.y = cvt_pk_bf16(o1[0], o1[1]); w.z = cvt_pk_bf16(o2[0], o2[1]); w.w = cvt_pk_bf16(o3[0], o3[1]);
;                 *(LAS u32x4*)(XC + (tr * 8 + j) * XC_PITCH + cgp * 16) = w;
;             }
	v_pk_fma_f32 v[66:67], v[60:61], v[66:67], v[124:125]
	v_pk_fma_f32 v[154:155], v[62:63], v[154:155], v[126:127]
	v_pk_fma_f32 v[168:169], v[52:53], v[168:169], v[120:121]
	v_lshlrev_b32_e32 v170, 16, v71
	v_and_b32_e32 v171, 0xffff0000, v71
	v_lshlrev_b32_e32 v172, 16, v72
	v_and_b32_e32 v173, 0xffff0000, v72
	v_lshlrev_b32_e32 v174, 16, v73
	v_and_b32_e32 v175, 0xffff0000, v73
	v_lshlrev_b32_e32 v176, 16, v74
	v_and_b32_e32 v177, 0xffff0000, v74
	v_pk_fma_f32 v[170:171], v[54:55], v[170:171], v[122:123]
	v_pk_fma_f32 v[66:67], v[56:57], v[172:173], v[66:67]
	v_pk_fma_f32 v[154:155], v[58:59], v[174:175], v[154:155]
	v_pk_fma_f32 v[168:169], v[44:45], v[176:177], v[168:169]
	v_lshlrev_b32_e32 v178, 16, v75
	v_and_b32_e32 v179, 0xffff0000, v75
	v_lshlrev_b32_e32 v180, 16, v76
	v_and_b32_e32 v181, 0xffff0000, v76
	v_lshlrev_b32_e32 v182, 16, v77
	v_and_b32_e32 v183, 0xffff0000, v77
	v_lshlrev_b32_e32 v184, 16, v78
	v_and_b32_e32 v185, 0xffff0000, v78
	v_pk_fma_f32 v[170:171], v[46:47], v[178:179], v[170:171]
	v_pk_fma_f32 v[66:67], v[48:49], v[180:181], v[66:67]
	v_pk_fma_f32 v[154:155], v[50:51], v[182:183], v[154:155]
	v_pk_fma_f32 v[168:169], v[40:41], v[184:185], v[168:169]
	v_lshlrev_b32_e32 v186, 16, v79
	v_and_b32_e32 v187, 0xffff0000, v79
	v_lshlrev_b32_e32 v188, 16, v80
	v_and_b32_e32 v189, 0xffff0000, v80
	v_lshlrev_b32_e32 v190, 16, v81
	v_and_b32_e32 v191, 0xffff0000, v81
	v_lshlrev_b32_e32 v192, 16, v82
	v_and_b32_e32 v193, 0xffff0000, v82
	v_pk_fma_f32 v[170:171], v[42:43], v[186:187], v[170:171]
	s_waitcnt lgkmcnt(0)
	v_pk_fma_f32 v[66:67], v[36:37], v[188:189], v[66:67]
	v_pk_fma_f32 v[154:155], v[38:39], v[190:191], v[154:155]
	v_pk_fma_f32 v[194:195], v[32:33], v[192:193], v[168:169]
	v_lshlrev_b32_e32 v196, 16, v83
	v_and_b32_e32 v197, 0xffff0000, v83
	v_cvt_pk_bf16_f32 v168, v66, v67
	v_cvt_pk_bf16_f32 v169, v154, v155
	v_pk_fma_f32 v[198:199], v[34:35], v[196:197], v[170:171]
	v_cvt_pk_bf16_f32 v170, v194, v195
	v_pk_fma_f32 v[66:67], v[60:61], v[172:173], v[124:125]
	v_cvt_pk_bf16_f32 v171, v198, v199
	ds_write_b128 v151, v[168:171]
	v_pk_fma_f32 v[154:155], v[62:63], v[174:175], v[126:127]
	v_pk_fma_f32 v[168:169], v[52:53], v[176:177], v[120:121]
	v_pk_fma_f32 v[170:171], v[54:55], v[178:179], v[122:123]
	v_pk_fma_f32 v[66:67], v[56:57], v[180:181], v[66:67]
	v_pk_fma_f32 v[154:155], v[58:59], v[182:183], v[154:155]
	v_pk_fma_f32 v[168:169], v[44:45], v[184:185], v[168:169]
	v_pk_fma_f32 v[170:171], v[46:47], v[186:187], v[170:171]
	v_pk_fma_f32 v[66:67], v[48:49], v[188:189], v[66:67]
	v_pk_fma_f32 v[154:155], v[50:51], v[190:191], v[154:155]
	v_pk_fma_f32 v[168:169], v[40:41], v[192:193], v[168:169]
	v_lshlrev_b32_e32 v172, 16, v84
	v_and_b32_e32 v173, 0xffff0000, v84
	v_lshlrev_b32_e32 v174, 16, v85
	v_and_b32_e32 v175, 0xffff0000, v85
	v_lshlrev_b32_e32 v176, 16, v86
	v_and_b32_e32 v177, 0xffff0000, v86
	v_pk_fma_f32 v[170:171], v[42:43], v[196:197], v[170:171]
	v_pk_fma_f32 v[66:67], v[36:37], v[172:173], v[66:67]
	v_pk_fma_f32 v[154:155], v[38:39], v[174:175], v[154:155]
	v_pk_fma_f32 v[178:179], v[32:33], v[176:177], v[168:169]
	v_lshlrev_b32_e32 v194, 16, v87
	v_and_b32_e32 v195, 0xffff0000, v87
	v_cvt_pk_bf16_f32 v168, v66, v67
	v_cvt_pk_bf16_f32 v169, v154, v155
	v_pk_fma_f32 v[198:199], v[34:35], v[194:195], v[170:171]
	v_cvt_pk_bf16_f32 v170, v178, v179
	v_pk_fma_f32 v[66:67], v[60:61], v[180:181], v[124:125]
	v_cvt_pk_bf16_f32 v171, v198, v199
	ds_write_b128 v151, v[168:171] offset:272
	v_pk_fma_f32 v[154:155], v[62:63], v[182:183], v[126:127]
	v_pk_fma_f32 v[168:169], v[52:53], v[184:185], v[120:121]
	v_pk_fma_f32 v[170:171], v[54:55], v[186:187], v[122:123]
	v_pk_fma_f32 v[66:67], v[56:57], v[188:189], v[66:67]
	v_pk_fma_f32 v[154:155], v[58:59], v[190:191], v[154:155]
	v_pk_fma_f32 v[168:169], v[44:45], v[192:193], v[168:169]
	v_pk_fma_f32 v[170:171], v[46:47], v[196:197], v[170:171]
	v_pk_fma_f32 v[66:67], v[48:49], v[172:173], v[66:67]
	v_pk_fma_f32 v[154:155], v[50:51], v[174:175], v[154:155]
	v_pk_fma_f32 v[168:169], v[40:41], v[176:177], v[168:169]
	v_lshlrev_b32_e32 v178, 16, v88
	v_and_b32_e32 v179, 0xffff0000, v88
	v_lshlrev_b32_e32 v180, 16, v89
	v_and_b32_e32 v181, 0xffff0000, v89
	v_lshlrev_b32_e32 v182, 16, v90
	v_and_b32_e32 v183, 0xffff0000, v90
	v_pk_fma_f32 v[170:171], v[42:43], v[194:195], v[170:171]
	v_pk_fma_f32 v[66:67], v[36:37], v[178:179], v[66:67]
	v_pk_fma_f32 v[154:155], v[38:39], v[180:181], v[154:155]
	v_pk_fma_f32 v[184:185], v[32:33], v[182:183], v[168:169]
	v_lshlrev_b32_e32 v186, 16, v91
	v_and_b32_e32 v187, 0xffff0000, v91
	v_cvt_pk_bf16_f32 v168, v66, v67
	v_cvt_pk_bf16_f32 v169, v154, v155
	v_pk_fma_f32 v[198:199], v[34:35], v[186:187], v[170:171]
	v_cvt_pk_bf16_f32 v170, v184, v185
	v_pk_fma_f32 v[66:67], v[60:61], v[188:189], v[124:125]
	v_cvt_pk_bf16_f32 v171, v198, v199
	ds_write_b128 v151, v[168:171] offset:544
	v_pk_fma_f32 v[154:155], v[62:63], v[190:191], v[126:127]
	v_pk_fma_f32 v[168:169], v[52:53], v[192:193], v[120:121]
	v_pk_fma_f32 v[170:171], v[54:55], v[196:197], v[122:123]
	v_pk_fma_f32 v[66:67], v[56:57], v[172:173], v[66:67]
	v_pk_fma_f32 v[154:155], v[58:59], v[174:175], v[154:155]
	v_pk_fma_f32 v[168:169], v[44:45], v[176:177], v[168:169]
	v_pk_fma_f32 v[170:171], v[46:47], v[194:195], v[170:171]
	v_pk_fma_f32 v[66:67], v[48:49], v[178:179], v[66:67]
	v_pk_fma_f32 v[154:155], v[50:51], v[180:181], v[154:155]
	v_pk_fma_f32 v[168:169], v[40:41], v[182:183], v[168:169]
	v_lshlrev_b32_e32 v184, 16, v92
	v_and_b32_e32 v185, 0xffff0000, v92
	v_lshlrev_b32_e32 v188, 16, v93
	v_and_b32_e32 v189, 0xffff0000, v93
	v_lshlrev_b32_e32 v190, 16, v94
; #define LAS __attribute__((address_space(3)))
; __device__ __forceinline__ unsigned cvt_pk_bf16(float lo, float hi) { unsigned r; asm volatile("v_cvt_pk_bf16_f32 %0, %1, %2" : "=v"(r) : "v"(lo), "v"(hi)); return r; }
; __device__ __forceinline__ float bf_lo(unsigned u) { return __uint_as_float(u << 16); }
; __device__ __forceinline__ float bf_hi(unsigned u) { return __uint_as_float(u & 0xffff0000u); }
; template <int dir>
; __device__ __forceinline__ void lru_pass(LAS unsigned char* lds, const Params& P, int b, int h, int q, bool dry) {
;     ...
;             for (int j = 0; j < 8; ++j) {
;                 f32x2 o0 = cb2[0], o1 = cb2[1], o2 = cb2[2], o3 = cb2[3];
; #pragma unroll
;                 for (int k = 0; k < 4; ++k) { const u32x4 rr = rows[j + k];
;                     o0 = cw2[k][0] * (f32x2){bf_lo(rr.x), bf_hi(rr.x)} + o0; o1 = cw2[k][1] * (f32x2){bf_lo(rr.y), bf_hi(rr.y)} + o1;
;                     o2 = cw2[k][2] * (f32x2){bf_lo(rr.z), bf_hi(rr.z)} + o2; o3 = cw2[k][3] * (f32x2){bf_lo(rr.w), bf_hi(rr.w)} + o3; }
;                 u32x4 w; w.x = cvt_pk_bf16(o0[0], o0[1]); w.y = cvt_pk_bf16(o1[0], o1[1]); w.z = cvt_pk_bf16(o2[0], o2[1]); w.w = cvt_pk_bf16(o3[0], o3[1]);
;                 *(LAS u32x4*)(XC + (tr * 8 + j) * XC_PITCH + cgp * 16) = w;
;             }
	v_and_b32_e32 v191, 0xffff0000, v94
	v_pk_fma_f32 v[170:171], v[42:43], v[186:187], v[170:171]
	v_pk_fma_f32 v[66:67], v[36:37], v[184:185], v[66:67]
	v_pk_fma_f32 v[154:155], v[38:39], v[188:189], v[154:155]
	v_pk_fma_f32 v[192:193], v[32:33], v[190:191], v[168:169]
	v_lshlrev_b32_e32 v196, 16, v95
	v_and_b32_e32 v197, 0xffff0000, v95
	v_cvt_pk_bf16_f32 v168, v66, v67
	v_cvt_pk_bf16_f32 v169, v154, v155
	v_pk_fma_f32 v[198:199], v[34:35], v[196:197], v[170:171]
	v_cvt_pk_bf16_f32 v170, v192, v193
	v_pk_fma_f32 v[66:67], v[60:61], v[172:173], v[124:125]
	v_cvt_pk_bf16_f32 v171, v198, v199
	ds_write_b128 v151, v[168:171] offset:816
	v_pk_fma_f32 v[154:155], v[62:63], v[174:175], v[126:127]
	v_pk_fma_f32 v[168:169], v[52:53], v[176:177], v[120:121]
	v_pk_fma_f32 v[170:171], v[54:55], v[194:195], v[122:123]
	v_pk_fma_f32 v[66:67], v[56:57], v[178:179], v[66:67]
	v_pk_fma_f32 v[154:155], v[58:59], v[180:181], v[154:155]
	v_pk_fma_f32 v[168:169], v[44:45], v[182:183], v[168:169]
	v_pk_fma_f32 v[170:171], v[46:47], v[186:187], v[170:171]
	v_pk_fma_f32 v[66:67], v[48:49], v[184:185], v[66:67]
	v_pk_fma_f32 v[154:155], v[50:51], v[188:189], v[154:155]
	v_pk_fma_f32 v[168:169], v[40:41], v[190:191], v[168:169]
	v_lshlrev_b32_e32 v172, 16, v96
	v_and_b32_e32 v173, 0xffff0000, v96
	v_lshlrev_b32_e32 v174, 16, v97
	v_and_b32_e32 v175, 0xffff0000, v97
	v_lshlrev_b32_e32 v176, 16, v98
	v_and_b32_e32 v177, 0xffff0000, v98
	v_pk_fma_f32 v[170:171], v[42:43], v[196:197], v[170:171]
	v_pk_fma_f32 v[66:67], v[36:37], v[172:173], v[66:67]
	v_pk_fma_f32 v[154:155], v[38:39], v[174:175], v[154:155]
	v_pk_fma_f32 v[192:193], v[32:33], v[176:177], v[168:169]
	v_lshlrev_b32_e32 v194, 16, v99
	v_and_b32_e32 v195, 0xffff0000, v99
	v_cvt_pk_bf16_f32 v168, v66, v67
	v_cvt_pk_bf16_f32 v169, v154, v155
	v_pk_fma_f32 v[198:199], v[34:35], v[194:195], v[170:171]
	v_cvt_pk_bf16_f32 v170, v192, v193
	v_pk_fma_f32 v[66:67], v[60:61], v[178:179], v[124:125]
	v_cvt_pk_bf16_f32 v171, v198, v199
	ds_write_b128 v151, v[168:171] offset:1088
	v_pk_fma_f32 v[154:155], v[62:63], v[180:181], v[126:127]
	v_pk_fma_f32 v[168:169], v[52:53], v[182:183], v[120:121]
	v_pk_fma_f32 v[170:171], v[54:55], v[186:187], v[122:123]
	v_pk_fma_f32 v[66:67], v[56:57], v[184:185], v[66:67]
	v_pk_fma_f32 v[154:155], v[58:59], v[188:189], v[154:155]
	v_pk_fma_f32 v[168:169], v[44:45], v[190:191], v[168:169]
	v_pk_fma_f32 v[170:171], v[46:47], v[196:197], v[170:171]
	v_pk_fma_f32 v[66:67], v[48:49], v[172:173], v[66:67]
	v_pk_fma_f32 v[154:155], v[50:51], v[174:175], v[154:155]
	v_pk_fma_f32 v[168:169], v[40:41], v[176:177], v[168:169]
	v_lshlrev_b32_e32 v178, 16, v100
	v_and_b32_e32 v179, 0xffff0000, v100
	v_lshlrev_b32_e32 v180, 16, v101
	v_and_b32_e32 v181, 0xffff0000, v101
	v_lshlrev_b32_e32 v182, 16, v102
	v_and_b32_e32 v183, 0xffff0000, v102
	v_pk_fma_f32 v[170:171], v[42:43], v[194:195], v[170:171]
	v_pk_fma_f32 v[66:67], v[36:37], v[178:179], v[66:67]
	v_pk_fma_f32 v[154:155], v[38:39], v[180:181], v[154:155]
	v_pk_fma_f32 v[186:187], v[32:33], v[182:183], v[168:169]
	v_lshlrev_b32_e32 v192, 16, v103
	v_and_b32_e32 v193, 0xffff0000, v103
	v_cvt_pk_bf16_f32 v168, v66, v67
	v_cvt_pk_bf16_f32 v169, v154, v155
	s_and_b64 s[18:19], s[18:19], s[20:21]
	v_pk_fma_f32 v[198:199], v[34:35], v[192:193], v[170:171]
	v_cvt_pk_bf16_f32 v170, v186, v187
	v_pk_fma_f32 v[66:67], v[60:61], v[184:185], v[124:125]
	v_cvt_pk_bf16_f32 v171, v198, v199
	ds_write_b128 v151, v[168:171] offset:1360
	v_pk_fma_f32 v[168:169], v[52:53], v[190:191], v[120:121]
	v_pk_fma_f32 v[60:61], v[60:61], v[172:173], v[124:125]
	v_pk_fma_f32 v[52:53], v[52:53], v[176:177], v[120:121]
	s_waitcnt vmcnt(0)
	v_cndmask_b32_e64 v108, 0, v108, s[18:19]
	v_pk_fma_f32 v[154:155], v[62:63], v[188:189], v[126:127]
	v_pk_fma_f32 v[66:67], v[56:57], v[172:173], v[66:67]
	v_pk_fma_f32 v[168:169], v[44:45], v[176:177], v[168:169]
	v_lshlrev_b32_e32 v184, 16, v104
	v_and_b32_e32 v185, 0xffff0000, v104
	v_lshlrev_b32_e32 v188, 16, v106
	v_and_b32_e32 v189, 0xffff0000, v106
	v_pk_fma_f32 v[62:63], v[62:63], v[174:175], v[126:127]
	v_pk_fma_f32 v[56:57], v[56:57], v[178:179], v[60:61]
	v_pk_fma_f32 v[44:45], v[44:45], v[182:183], v[52:53]
	v_cndmask_b32_e64 v109, 0, v109, s[18:19]
	v_pk_fma_f32 v[154:155], v[58:59], v[174:175], v[154:155]
	v_pk_fma_f32 v[66:67], v[48:49], v[178:179], v[66:67]
	v_pk_fma_f32 v[168:169], v[40:41], v[182:183], v[168:169]
	v_lshlrev_b32_e32 v186, 16, v105
	v_and_b32_e32 v187, 0xffff0000, v105
	v_pk_fma_f32 v[58:59], v[58:59], v[180:181], v[62:63]
	v_pk_fma_f32 v[48:49], v[48:49], v[184:185], v[56:57]
	v_pk_fma_f32 v[40:41], v[40:41], v[188:189], v[44:45]
	v_lshlrev_b32_e32 v44, 16, v108
	v_and_b32_e32 v45, 0xffff0000, v108
	v_cndmask_b32_e64 v110, 0, v110, s[18:19]
	v_pk_fma_f32 v[170:171], v[54:55], v[196:197], v[122:123]
	v_pk_fma_f32 v[154:155], v[50:51], v[180:181], v[154:155]
	v_pk_fma_f32 v[66:67], v[36:37], v[184:185], v[66:67]
	v_pk_fma_f32 v[54:55], v[54:55], v[194:195], v[122:123]
	v_pk_fma_f32 v[50:51], v[50:51], v[186:187], v[58:59]
	v_pk_fma_f32 v[36:37], v[36:37], v[44:45], v[48:49]
	v_lshlrev_b32_e32 v44, 16, v109
	v_and_b32_e32 v45, 0xffff0000, v109
	v_cndmask_b32_e64 v111, 0, v111, s[18:19]
	v_pk_fma_f32 v[170:171], v[46:47], v[194:195], v[170:171]
	v_pk_fma_f32 v[154:155], v[38:39], v[186:187], v[154:155]
	v_lshlrev_b32_e32 v196, 16, v107
	v_and_b32_e32 v197, 0xffff0000, v107
	v_pk_fma_f32 v[46:47], v[46:47], v[192:193], v[54:55]
	v_pk_fma_f32 v[38:39], v[38:39], v[44:45], v[50:51]
	v_lshlrev_b32_e32 v44, 16, v110
	v_and_b32_e32 v45, 0xffff0000, v110
	v_pk_fma_f32 v[170:171], v[42:43], v[192:193], v[170:171]
	v_pk_fma_f32 v[190:191], v[32:33], v[188:189], v[168:169]
	v_pk_fma_f32 v[42:43], v[42:43], v[196:197], v[46:47]
	v_pk_fma_f32 v[40:41], v[32:33], v[44:45], v[40:41]
	v_lshlrev_b32_e32 v32, 16, v111
	v_and_b32_e32 v33, 0xffff0000, v111
	v_pk_fma_f32 v[198:199], v[34:35], v[196:197], v[170:171]
	v_cvt_pk_bf16_f32 v168, v66, v67
	v_cvt_pk_bf16_f32 v169, v154, v155
	v_cvt_pk_bf16_f32 v170, v190, v191
	v_pk_fma_f32 v[42:43], v[34:35], v[32:33], v[42:43]
	v_cvt_pk_bf16_f32 v171, v198, v199
	ds_write_b128 v151, v[168:171] offset:1632
	v_cvt_pk_bf16_f32 v32, v36, v37
	v_cvt_pk_bf16_f32 v33, v38, v39
	v_cvt_pk_bf16_f32 v34, v40, v41
	v_cvt_pk_bf16_f32 v35, v42, v43
	s_cmp_eq_u32 s80, 0x80000
	ds_write_b128 v151, v[32:35] offset:1904
	ds_write_b128 v158, v[112:115]
	ds_write_b128 v159, v[116:119]
	s_cbranch_scc1 .LBB0_294
; template <int dir>
; __device__ __forceinline__ void lru_pass(LAS unsigned char* lds, const Params& P, int b, int h, int q, bool dry) {
;     ...
;             LruTile nxt = cur;
;             if (sc < 8) { nxt = lru_tile(Z, ZC, b, h, dir, sc + 1); lru_load_rows(rows, nxt, tr, cgp);
; #pragma unroll
;                 for (int i = 0; i < NIN; ++i) { const int id = tid + i * NTHREADS;
;                     if (dir == 0) inr[i] = *(const u32x4*)(Zg + (size_t)(nxt.t0 + (id >> 2)) * 128 + (id & 3) * 8);
;                     else inr[i] = *(const u32x4*)(Hg + (size_t)(nxt.t0 + (id >> 3)) * DM + (id & 7) * 4); } }
	v_lshl_add_u64 v[32:33], v[136:137], 0, s[80:81]
	global_load_dwordx4 v[68:71], v[32:33], off offset:-1280
	global_load_dwordx4 v[72:75], v[32:33], off offset:-1024
	global_load_dwordx4 v[76:79], v[32:33], off offset:-768
	global_load_dwordx4 v[80:83], v[32:33], off offset:-512
	global_load_dwordx4 v[84:87], v[32:33], off offset:-256
	global_load_dwordx4 v[88:91], v[32:33], off
	global_load_dwordx4 v[92:95], v[32:33], off offset:256
	global_load_dwordx4 v[96:99], v[32:33], off offset:512
	global_load_dwordx4 v[100:103], v[32:33], off offset:768
	global_load_dwordx4 v[104:107], v[32:33], off offset:1024
	v_lshl_add_u64 v[34:35], v[134:135], 0, s[80:81]
	global_load_dwordx4 v[108:111], v[32:33], off offset:1280
	global_load_dwordx4 v[112:115], v[34:35], off
	v_lshl_add_u64 v[32:33], v[132:133], 0, s[80:81]
	global_load_dwordx4 v[116:119], v[32:33], off
	s_movk_i32 s92, 0x800
	s_mov_b32 s20, s90
	s_branch .LBB0_295

; #define LAS __attribute__((address_space(3)))
; __device__ __forceinline__ int opaque_tid() { int t = threadIdx.x; asm volatile("" : "+v"(t)); return t; }
; template <int dir>
; __device__ __forceinline__ void lru_pass(LAS unsigned char* lds, const Params& P, int b, int h, int q, bool dry) {
;     const int tid = opaque_tid(), lane = tid & 63, wid = __builtin_amdgcn_readfirstlane(tid >> 6), g = lane >> 5, nl = lane & 31;
;     const int chl = q * 32 + nl, ch = h * 128 + chl;
;     LAS unsigned char* XC = lds;
;     LAS float* AGG = (LAS float*)(lds + 256 * XC_PITCH);
;     LAS unsigned char* WB = lds + 256 * XC_PITCH + 2048;
;     LAS float* CWL = (LAS float*)(lds + 256 * XC_PITCH + 2048 + 64 * XC_PITCH);
;     LAS unsigned char* TIN = lds + LRU_IO_OFF;
;     LAS unsigned char* TOUT = lds + LRU_IO_OFF + 256 * (dir == 0 ? IO_NP : IO_WP);
;     bf16_t* Z = (bf16_t*)(P.ws + WS_Z); const bf16_t* ZC = (const bf16_t*)(P.ws + WS_ZC); unsigned* HFW = (unsigned*)(P.ws + WS_HF);
;     const bf16_t* LruW = (const bf16_t*)(P.ws + WS_LRUW);
;     const int cgp = tid & 15, tr = tid >> 4;
;     const int s_i = 16 * ((nl >> 2) & 1) + ((nl >> 3) << 2) + (nl & 3);
;     const bf16_t* Zg = Z + ZSLAB(8 + h, (size_t)b * SEQ) + q * 32;
;     unsigned* Hg = HFW + (size_t)b * SEQ * DM + h * 128 + q * 32;
;     {
; #pragma unroll
;         for (int i = 0; i < 2; ++i) { const int idx = tid + i * NTHREADS, gate = idx >> 9, n = (idx >> 4) & 31, kc = idx & 15;
;             *(LAS u32x4*)(WB + (gate * 32 + n) * XC_PITCH + kc * 16) = *(const u32x4*)(LruW + ((size_t)((dir * 2 + gate) * 8 + h) * 128 + q * 32 + n) * 128 + kc * 8); }
;         const float br = -LOG2E * P.lru_ba[(dir * 8 + h) * 128 + chl], bi = -LOG2E * P.lru_bx[(dir * 8 + h) * 128 + chl];
;         const float lam = P.lru_lambda[dir * 1024 + ch];
;         const float cl = -8.0f * LOG2E * log1pf(__expf(-lam));
;         float carry = 0.f;
;         LruTile cur = lru_tile(Z, ZC, b, h, dir, 0);
;         u32x4 rows[11];
;         constexpr int NIN = dir == 0 ? 2 : 4;
;         u32x4 inr[NIN];
;         lru_load_rows(rows, cur, tr, cgp);
;     ...
;         if (dir == 0) {
; #pragma unroll
;             for (int i = 0; i < 4; ++i) { const int id = tid + i * NTHREADS; *(u32x4*)(Hg + (size_t)(t0_prev + (id >> 3)) * DM + (id & 7) * 4) = *(const LAS u32x4*)(TOUT + (id >> 3) * IO_WP + (id & 7) * 16); }
.Lpp_f_noy:
	s_waitcnt lgkmcnt(0)
	s_barrier
	v_add_u32_e32 v0, v129, v149
	ds_read_b128 v[0:3], v0
	v_add_u32_e32 v4, s97, v148
	v_ashrrev_i32_e32 v5, 31, v4
	v_lshlrev_b64 v[4:5], 12, v[4:5]
	v_lshl_add_u64 v[8:9], v[130:131], 0, v[4:5]
	v_add_u32_e32 v4, v129, v146
	ds_read_b128 v[4:7], v4
	s_waitcnt lgkmcnt(1)
	global_store_dwordx4 v[8:9], v[0:3], off
	v_cmp_gt_i32_e32 vcc, 64, v128
	s_nop 0
	v_add_u32_e32 v0, s97, v145
	v_ashrrev_i32_e32 v1, 31, v0
	v_lshlrev_b64 v[0:1], 12, v[0:1]
	v_lshl_add_u64 v[0:1], v[130:131], 0, v[0:1]
	s_waitcnt lgkmcnt(0)
	global_store_dwordx4 v[0:1], v[4:7], off
	v_add_u32_e32 v0, v129, v144
	ds_read_b128 v[0:3], v0
	v_add_u32_e32 v4, s97, v143
	v_ashrrev_i32_e32 v5, 31, v4
	v_lshlrev_b64 v[4:5], 12, v[4:5]
	v_lshl_add_u64 v[8:9], v[130:131], 0, v[4:5]
	v_add_u32_e32 v4, v129, v142
	ds_read_b128 v[4:7], v4
	s_waitcnt lgkmcnt(1)
	global_store_dwordx4 v[8:9], v[0:3], off
	s_nop 1
	v_add_u32_e32 v0, s97, v141
	v_ashrrev_i32_e32 v1, 31, v0
	v_lshlrev_b64 v[0:1], 12, v[0:1]
	v_lshl_add_u64 v[0:1], v[130:131], 0, v[0:1]
	s_waitcnt lgkmcnt(0)
	global_store_dwordx4 v[0:1], v[4:7], off
	s_waitcnt lgkmcnt(0)
	v_mov_b32_e32 v32, v167
	s_barrier
	s_or_b32 s0, s26, 16
	v_and_b32_e32 v15, 31, v32
	v_or_b32_e32 v17, s28, v15
	v_add_u32_e32 v13, 0x200, v32
	v_or_b32_e32 v8, s27, v17
	v_ashrrev_i32_e32 v11, 9, v32
	v_ashrrev_i32_e32 v14, 9, v13
	v_lshlrev_b32_e32 v8, 2, v8
	v_mov_b32_e32 v9, v65
	v_lshl_add_u32 v2, v11, 3, s0
	v_lshl_add_u32 v6, v14, 3, s0
	v_lshl_add_u64 v[8:9], s[64:65], 0, v[8:9]
	s_movk_i32 s0, 0x1000
	v_add_co_u32_e32 v8, vcc, s0, v8
	v_and_b32_e32 v12, 15, v32
	s_nop 0
	v_addc_co_u32_e32 v9, vcc, 0, v9, vcc
	global_load_dword v16, v[8:9], off
	v_bfe_u32 v10, v32, 4, 5
	v_lshlrev_b32_e32 v64, 4, v12
	v_ashrrev_i32_e32 v3, 31, v2
	v_ashrrev_i32_e32 v7, 31, v6
	v_or_b32_e32 v4, s28, v10
	v_lshl_add_u64 v[0:1], s[38:39], 0, v[64:65]
	v_lshlrev_b64 v[2:3], 15, v[2:3]
	v_lshlrev_b64 v[6:7], 15, v[6:7]
	v_lshlrev_b32_e32 v4, 8, v4
	v_mov_b32_e32 v5, v65
	v_lshl_add_u64 v[2:3], v[0:1], 0, v[2:3]
	v_lshl_add_u64 v[0:1], v[0:1], 0, v[6:7]
	v_lshl_add_u64 v[2:3], v[2:3], 0, v[4:5]
	v_lshl_add_u64 v[4:5], v[0:1], 0, v[4:5]
	global_load_dwordx4 v[0:3], v[2:3], off
	s_nop 0
	global_load_dwordx4 v[4:7], v[4:5], off
	v_lshrrev_b32_e32 v8, 1, v32
	v_lshlrev_b32_e32 v9, 2, v32
	v_and_b32_e32 v20, 12, v8
	v_lshl_or_b32 v11, v11, 5, v10
	v_add_u32_e32 v8, s88, v64
	v_lshl_or_b32 v14, v14, 5, v10
	v_mad_u64_u32 v[10:11], s[6:7], v11, s89, v[8:9]
	s_or_b32 s8, s26, 8
	v_and_or_b32 v20, v9, 16, v20
	v_lshlrev_b32_e32 v21, 2, v17
	v_mad_u64_u32 v[8:9], s[6:7], v14, s89, v[8:9]
	v_lshl_or_b32 v9, s8, 9, v21
	global_load_dword v14, v9, s[58:59]
	s_nop 0
	global_load_dword v9, v9, s[62:63]
	s_mov_b32 s80, 0x3f2aaaab
	s_mov_b32 s81, 0x3f317218
	s_mov_b32 s91, 0x7f800000
	s_mov_b32 s92, 0x33800000
	v_ashrrev_i32_e32 v33, 4, v32
	v_lshlrev_b32_e32 v34, 3, v12
	v_readfirstlane_b32 s4, v32
	s_lshl_b64 s[0:1], s[78:79], 11
	s_lshl_b32 s5, s8, 14
	s_ashr_i32 s6, s4, 6
	s_add_u32 s26, s0, s5
	s_addc_u32 s27, s1, 0
	s_lshl_b32 s0, s28, 1
	v_readlane_b32 s1, v255, 10
	v_and_b32_e32 v19, 3, v32
	s_add_u32 s0, s1, s0
	v_bfe_u32 v18, v32, 5, 1
	v_add_u32_e32 v44, 0, v64
	v_lshlrev_b32_e32 v64, 4, v19
	s_addc_u32 s1, s3, 0
	v_lshl_add_u64 v[136:137], s[0:1], 0, v[64:65]
	s_lshl_b32 s0, s6, 5
	v_lshlrev_b32_e32 v46, 4, v18
	v_or_b32_e32 v37, s0, v46
	v_add_u32_e32 v158, s86, v64
	v_or_b32_e32 v64, 4, v37
	s_movk_i32 s93, 0x880
	v_ashrrev_i32_e32 v36, 3, v32
	v_ashrrev_i32_e32 v38, 3, v13
	v_ashrrev_i32_e32 v140, 2, v32
	v_sub_u32_e32 v39, 0xff, v37
	v_sub_u32_e32 v64, 0xff, v64
	v_lshl_add_u32 v160, v33, 3, -1
	v_mul_lo_u32 v52, v33, s93
	v_lshl_or_b32 v110, v33, 13, v34
	v_mov_b32_e32 v111, v65
	v_lshlrev_b64 v[110:111], 1, v[110:111]
	v_lshl_add_u64 v[108:109], s[48:49], 0, v[110:111]
	global_load_dwordx4 v[68:71], v[108:109], off offset:-2048
	global_load_dwordx4 v[72:75], v[108:109], off
	global_load_dwordx4 v[76:79], v[108:109], off offset:2048
	v_lshl_add_u64 v[108:109], s[50:51], 0, v[110:111]
	global_load_dwordx4 v[80:83], v[108:109], off
	v_lshl_add_u64 v[108:109], s[56:57], 0, v[110:111]
	global_load_dwordx4 v[84:87], v[108:109], off
	v_lshl_add_u64 v[108:109], s[60:61], 0, v[110:111]
	global_load_dwordx4 v[88:91], v[108:109], off
	v_lshl_add_u64 v[108:109], s[66:67], 0, v[110:111]
	global_load_dwordx4 v[92:95], v[108:109], off
	v_lshl_add_u64 v[108:109], s[70:71], 0, v[110:111]
	global_load_dwordx4 v[96:99], v[108:109], off
	v_lshl_add_u64 v[108:109], s[72:73], 0, v[110:111]
	global_load_dwordx4 v[100:103], v[108:109], off
	v_lshl_add_u64 v[108:109], s[74:75], 0, v[110:111]
	global_load_dwordx4 v[104:107], v[108:109], off
	v_lshl_add_u64 v[108:109], s[76:77], 0, v[110:111]
	global_load_dwordx4 v[108:111], v[108:109], off
	s_waitcnt vmcnt(14)
	ds_write_b128 v10, v[0:3]
	s_waitcnt vmcnt(13)
; template <int dir>
; __device__ __forceinline__ void lru_pass(LAS unsigned char* lds, const Params& P, int b, int h, int q, bool dry) {
;     ...
;         const float br = -LOG2E * P.lru_ba[(dir * 8 + h) * 128 + chl], bi = -LOG2E * P.lru_bx[(dir * 8 + h) * 128 + chl];
;         const float lam = P.lru_lambda[dir * 1024 + ch];
;         const float cl = -8.0f * LOG2E * log1pf(__expf(-lam));
;         float carry = 0.f;
;         LruTile cur = lru_tile(Z, ZC, b, h, dir, 0);
;         u32x4 rows[11];
;         constexpr int NIN = dir == 0 ? 2 : 4;
;         u32x4 inr[NIN];
;         lru_load_rows(rows, cur, tr, cgp);
;     ...
;             const int sbase = 32 * wid + 16 * g;
;             { const int sl = 32 * wid + s_i; const int tlA = dir == 0 ? sl : 255 - sl;
;               const LAS unsigned char* ap = XC + tlA * XC_PITCH + 16 * g;
;               const LAS unsigned char* wrp = WB + nl * XC_PITCH + 16 * g; const LAS unsigned char* wip = wrp + 32 * XC_PITCH;
; #pragma unroll
;               for (int ks = 0; ks < 8; ++ks) { const bf16x8 A = *(const LAS bf16x8*)(ap + 32 * ks);
;                   const bf16x8 Br = *(const LAS bf16x8*)(wrp + 32 * ks), Bi = *(const LAS bf16x8*)(wip + 32 * ks);
;                   zr = __builtin_amdgcn_mfma_f32_32x32x16_bf16(A, Br, zr, 0, 0, 0); zi = __builtin_amdgcn_mfma_f32_32x32x16_bf16(A, Bi, zi, 0, 0, 0); } }
;             unsigned xcb[16], pk[16];
; #pragma unroll
;             for (int v = 0; v < 16; ++v) { const int s = sbase + v; const int tl = dir == 0 ? s : 255 - s; xcb[v] = *(const LAS bf16_t*)(XC + tl * XC_PITCH + chl * 2);
;                 if (dir == 0) pk[v] = *(const LAS bf16_t*)(TIN + tl * IO_NP + nl * 2); else pk[v] = *(const LAS unsigned*)(TIN + tl * IO_WP + nl * 4); }
;             float Pp = 1.f, E = 0.f;
; #pragma unroll
;             for (int v = 0; v < 16; ++v) {
;                 const float xcv = __uint_as_float(xcb[v] << 16);
;                 const float r = __builtin_amdgcn_rcpf(1.0f + __builtin_amdgcn_exp2f(zr[v]));
;                 const float ig = __builtin_amdgcn_rcpf(1.0f + __builtin_amdgcn_exp2f(zi[v]));
;                 const float a = __builtin_amdgcn_exp2f(cl * r);
;                 const float sq = __builtin_amdgcn_sqrtf(fmaf(-a, a, 1.0f));
;                 const float u = sq * ig * xcv;
;                 E = fmaf(a, E, u); Pp *= a; zr[v] = E; zi[v] = Pp; }
	ds_write_b128 v8, v[4:7]
	v_mul_f32_e32 v11, 0xbfb8aa3b, v16
	v_exp_f32_e32 v11, v11
	v_mul_lo_u32 v57, v39, s89
	v_mul_lo_u32 v58, v39, s30
	v_mul_lo_u32 v114, v64, s89
	v_add_f32_e32 v2, 1.0, v11
	v_add_f32_e32 v3, -1.0, v2
	v_frexp_mant_f32_e32 v4, v2
	v_cvt_f64_f32_e32 v[0:1], v2
	v_sub_f32_e32 v5, v3, v2
	v_frexp_exp_i32_f64_e32 v0, v[0:1]
	v_cmp_gt_f32_e32 vcc, s80, v4
	v_sub_f32_e32 v3, v11, v3
	v_add_f32_e32 v1, 1.0, v5
	v_subbrev_co_u32_e32 v0, vcc, 0, v0, vcc
	v_add_f32_e32 v1, v3, v1
	v_sub_u32_e32 v3, 0, v0
	v_ldexp_f32 v2, v2, v3
	v_ldexp_f32 v1, v1, v3
	v_add_f32_e32 v3, -1.0, v2
	v_add_f32_e32 v4, 1.0, v2
	v_add_f32_e32 v5, 1.0, v3
	v_add_f32_e32 v6, -1.0, v4
	v_sub_f32_e32 v5, v2, v5
	v_sub_f32_e32 v2, v2, v6
	v_add_f32_e32 v5, v1, v5
	v_add_f32_e32 v1, v1, v2
	v_add_f32_e32 v7, v4, v1
	v_rcp_f32_e32 v8, v7
	v_add_f32_e32 v2, v3, v5
	v_sub_f32_e32 v4, v7, v4
	v_sub_f32_e32 v3, v2, v3
	v_sub_f32_e32 v1, v1, v4
	v_mul_f32_e32 v4, v2, v8
	v_sub_f32_e32 v3, v5, v3
	v_mul_f32_e32 v5, v7, v4
	v_fma_f32 v10, v4, v7, -v5
	v_fmac_f32_e32 v10, v4, v1
	v_add_f32_e32 v16, v5, v10
	v_sub_f32_e32 v21, v2, v16
	v_sub_f32_e32 v2, v2, v21
	v_sub_f32_e32 v5, v16, v5
	v_sub_f32_e32 v2, v2, v16
	v_sub_f32_e32 v5, v5, v10
	v_add_f32_e32 v2, v3, v2
	v_add_f32_e32 v2, v5, v2
	v_add_f32_e32 v3, v21, v2
	v_mul_f32_e32 v5, v8, v3
	v_sub_f32_e32 v10, v21, v3
	v_mul_f32_e32 v16, v7, v5
	v_add_f32_e32 v2, v2, v10
	v_add_f32_e32 v10, v4, v5
	v_fma_f32 v7, v5, v7, -v16
	v_sub_f32_e32 v4, v10, v4
	v_fmac_f32_e32 v7, v5, v1
	v_sub_f32_e32 v1, v5, v4
	v_add_f32_e32 v4, v16, v7
	v_sub_f32_e32 v5, v4, v16
	v_sub_f32_e32 v16, v3, v4
	v_sub_f32_e32 v3, v3, v16
	v_sub_f32_e32 v3, v3, v4
	v_cvt_f32_i32_e32 v0, v0
	v_sub_f32_e32 v5, v5, v7
	v_add_f32_e32 v2, v2, v3
	v_add_f32_e32 v2, v5, v2
	v_add_f32_e32 v2, v16, v2
	v_mul_f32_e32 v2, v8, v2
	v_mul_f32_e32 v6, 0x3f317218, v0
	v_add_f32_e32 v1, v1, v2
	v_add_f32_e32 v2, v10, v1
	v_fma_f32 v5, v0, s81, -v6
	v_fmac_f32_e32 v5, 0xb102e308, v0
	v_sub_f32_e32 v0, v2, v10
	v_mul_f32_e32 v3, v2, v2
	v_sub_f32_e32 v0, v1, v0
	v_add_f32_e32 v1, v6, v5
	v_fmamk_f32 v4, v3, 0x3e9b6dac, v200
	v_sub_f32_e32 v6, v1, v6
	v_fmaak_f32 v4, v3, v4, 0x3f2aaada
	v_sub_f32_e32 v5, v5, v6
	v_ldexp_f32 v6, v2, 1
	v_mul_f32_e32 v2, v2, v3
	v_mul_f32_e32 v2, v2, v4
	v_add_f32_e32 v3, v6, v2
	v_sub_f32_e32 v4, v3, v6
	v_ldexp_f32 v0, v0, 1
	v_sub_f32_e32 v2, v2, v4
	v_add_f32_e32 v0, v0, v2
	v_add_f32_e32 v2, v3, v0
	v_sub_f32_e32 v3, v2, v3
	v_sub_f32_e32 v0, v0, v3
	v_add_f32_e32 v3, v1, v2
	v_sub_f32_e32 v4, v3, v1
	v_sub_f32_e32 v6, v3, v4
	v_sub_f32_e32 v1, v1, v6
	v_sub_f32_e32 v2, v2, v4
	v_add_f32_e32 v1, v2, v1
	v_add_f32_e32 v2, v5, v0
	v_sub_f32_e32 v4, v2, v5
	v_add_f32_e32 v1, v2, v1
	v_sub_f32_e32 v6, v2, v4
	v_add_f32_e32 v2, v3, v1
	v_sub_f32_e32 v5, v5, v6
	v_sub_f32_e32 v0, v0, v4
	v_sub_f32_e32 v3, v2, v3
	v_add_f32_e32 v0, v0, v5
	v_sub_f32_e32 v1, v1, v3
	v_add_f32_e32 v0, v0, v1
	v_add_f32_e32 v0, v2, v0
	v_cmp_neq_f32_e32 vcc, s91, v11
	v_mov_b32_e32 v1, v65
	v_mul_lo_u32 v115, v64, s30
	v_cndmask_b32_e32 v0, v201, v0, vcc
	v_cmp_ngt_f32_e32 vcc, -1.0, v11
	v_mul_lo_u32 v206, v39, s87
	v_mul_lo_u32 v210, v64, s87
	v_cndmask_b32_e32 v0, v202, v0, vcc
	v_cmp_neq_f32_e32 vcc, -1.0, v11
	v_ashrrev_i32_e32 v39, 31, v38
	v_sub_u32_e32 v41, 0xfe, v37
	v_cndmask_b32_e32 v0, v203, v0, vcc
	v_cmp_lt_f32_e64 vcc, |v11|, s92
	v_mul_lo_u32 v59, v41, s89
	v_mul_lo_u32 v60, v41, s30
	v_cndmask_b32_e32 v6, v0, v11, vcc
	v_lshlrev_b32_e32 v2, 4, v32
	v_and_b32_e32 v2, 0x70, v2
	v_lshlrev_b32_e32 v1, 2, v15
	v_add_u32_e32 v45, s95, v2
	v_or3_b32 v2, v19, v20, s0
	s_and_b32 s0, s4, 0x3fffffc0
	v_add_u32_e32 v161, s94, v1
	s_cmp_eq_u32 s6, 7
	v_lshl_add_u32 v254, s0, 2, v161
	s_cselect_b64 s[0:1], -1, 0
	s_cmp_eq_u32 s6, 6
	s_cselect_b64 s[16:17], -1, 0
	s_cmp_eq_u32 s6, 5
	s_cselect_b64 s[4:5], -1, 0
	s_cmp_eq_u32 s6, 4
	s_cselect_b64 s[8:9], -1, 0
	s_cmp_eq_u32 s6, 3
	s_cselect_b64 s[10:11], -1, 0
	s_cmp_eq_u32 s6, 2
	s_cselect_b64 s[12:13], -1, 0
	s_cmp_eq_u32 s6, 1
	s_cselect_b64 s[14:15], -1, 0
	s_lshl_b32 s6, s25, 7
	s_and_b32 s6, s6, 0xe00
	s_lshl_b32 s7, s29, 7
	s_or_b32 s6, s7, s6
	s_add_u32 s6, s6, s44
	v_add_u32_e32 v50, s95, v1
	v_add_u32_e32 v1, 0x400, v32
	s_addc_u32 s7, 0, s45
	v_ashrrev_i32_e32 v40, 3, v1
	v_add_u32_e32 v1, 0x600, v32
	v_and_b32_e32 v32, 7, v32
	s_add_u32 s18, s84, s46
	v_lshlrev_b32_e32 v64, 4, v32
	v_lshl_or_b32 v32, v33, 10, v34
	v_mov_b32_e32 v33, v65
	s_addc_u32 s19, s85, s47
	v_lshl_add_u64 v[144:145], v[32:33], 1, s[18:19]
	v_lshlrev_b64 v[32:33], 12, v[38:39]
	v_lshl_add_u64 v[32:33], s[6:7], 0, v[32:33]
	v_mul_lo_u32 v207, v41, s87
	v_lshl_add_u64 v[32:33], v[32:33], 0, v[64:65]
	v_ashrrev_i32_e32 v41, 31, v40
	v_or_b32_e32 v43, 2, v37
	v_lshl_add_u64 v[252:253], s[42:43], 0, v[32:33]
	v_lshlrev_b64 v[32:33], 12, v[40:41]
	v_ashrrev_i32_e32 v42, 3, v1
	v_sub_u32_e32 v43, 0xff, v43
	v_or_b32_e32 v63, 3, v37
	v_or_b32_e32 v66, 5, v37
	v_or_b32_e32 v67, 6, v37
	v_or_b32_e32 v120, 7, v37
	v_or_b32_e32 v123, 8, v37
	v_or_b32_e32 v126, 9, v37
	v_or_b32_e32 v129, 10, v37
	v_or_b32_e32 v132, 11, v37
	v_or_b32_e32 v135, 12, v37
	v_or_b32_e32 v142, 13, v37
	v_or_b32_e32 v143, 14, v37
	v_or_b32_e32 v37, 15, v37
	v_lshl_add_u64 v[32:33], s[6:7], 0, v[32:33]
	v_mul_lo_u32 v61, v43, s89
	v_mul_lo_u32 v62, v43, s30
	v_sub_u32_e32 v37, 0xff, v37
	v_mul_lo_u32 v208, v43, s87
	v_lshl_add_u64 v[32:33], v[32:33], 0, v[64:65]
	v_ashrrev_i32_e32 v43, 31, v42
	v_sub_u32_e32 v2, 0xff, v2
	v_mul_lo_u32 v204, v37, s89
	v_mul_lo_u32 v205, v37, s30
	v_mul_lo_u32 v221, v37, s87
	v_ashrrev_i32_e32 v37, 31, v36
	v_lshl_add_u64 v[154:155], s[42:43], 0, v[32:33]
	v_lshlrev_b64 v[32:33], 12, v[42:43]
	v_mul_lo_u32 v2, v2, s89
	v_mul_lo_u32 v53, v36, s30
	v_sub_u32_e32 v63, 0xff, v63
	v_sub_u32_e32 v66, 0xff, v66
	v_sub_u32_e32 v67, 0xff, v67
	v_sub_u32_e32 v120, 0xff, v120
	v_sub_u32_e32 v123, 0xff, v123
	v_sub_u32_e32 v126, 0xff, v126
	v_lshlrev_b64 v[36:37], 12, v[36:37]
	v_lshl_add_u64 v[32:33], s[6:7], 0, v[32:33]
	v_lshlrev_b32_e32 v35, 4, v12
	v_add_u32_e32 v47, 0, v2
	v_mov_b32_e32 v2, s88
	v_lshl_add_u32 v49, v17, 1, 0
	v_lshl_add_u32 v51, v15, 1, s86
	v_mul_lo_u32 v112, v63, s89
	v_mul_lo_u32 v113, v63, s30
	v_mul_lo_u32 v116, v66, s89
	v_mul_lo_u32 v117, v66, s30
	v_mul_lo_u32 v118, v67, s89
	v_mul_lo_u32 v119, v67, s30
	v_mul_lo_u32 v121, v120, s89
	v_mul_lo_u32 v122, v120, s30
	v_mul_lo_u32 v124, v123, s89
	v_mul_lo_u32 v125, v123, s30
	v_mul_lo_u32 v127, v126, s89
	v_mul_lo_u32 v128, v126, s30
	v_sub_u32_e32 v129, 0xff, v129
	v_sub_u32_e32 v132, 0xff, v132
	v_sub_u32_e32 v135, 0xff, v135
	v_sub_u32_e32 v142, 0xff, v142
	v_sub_u32_e32 v143, 0xff, v143
	v_mul_lo_u32 v211, v66, s87
	v_mul_lo_u32 v212, v67, s87
	v_mul_lo_u32 v120, v120, s87
	v_mul_lo_u32 v123, v123, s87
	v_mul_lo_u32 v126, v126, s87
	v_lshl_add_u64 v[36:37], s[6:7], 0, v[36:37]
	v_lshl_add_u64 v[32:33], v[32:33], 0, v[64:65]
	v_mov_b32_e32 v66, v65
	v_mov_b32_e32 v67, v65
	s_waitcnt vmcnt(12)
; #define LAS __attribute__((address_space(3)))
; template <int dir>
; __device__ __forceinline__ void lru_pass(LAS unsigned char* lds, const Params& P, int b, int h, int q, bool dry) {
;     ...
;         const float br = -LOG2E * P.lru_ba[(dir * 8 + h) * 128 + chl], bi = -LOG2E * P.lru_bx[(dir * 8 + h) * 128 + chl];
;         const float lam = P.lru_lambda[dir * 1024 + ch];
;         const float cl = -8.0f * LOG2E * log1pf(__expf(-lam));
;         float carry = 0.f;
;         LruTile cur = lru_tile(Z, ZC, b, h, dir, 0);
;         u32x4 rows[11];
;         constexpr int NIN = dir == 0 ? 2 : 4;
;         u32x4 inr[NIN];
;         lru_load_rows(rows, cur, tr, cgp);
; #pragma unroll
;         for (int i = 0; i < NIN; ++i) inr[i] = (u32x4){0u, 0u, 0u, 0u};
;         int t0_prev = 0;
;         for (int sc = 0; sc < 9; ++sc) {
;             const bool isctx = (sc == 0);
;             const int t0 = cur.t0;
; #pragma unroll
;             for (int j = 0; j < 11; ++j) { if (j != 0 && j < 9) continue;
;                 const int t = t0 + tr * 8 - 1 + j; if (t < 0 || t >= cur.L) rows[j] = (u32x4){0u, 0u, 0u, 0u}; }
;             f32x2 cw2[4][4], cb2[4];
; #pragma unroll
;             for (int k = 0; k < 5; ++k) { const f32x4 a = *(const LAS f32x4*)(CWL + k * 128 + cgp * 8), c2 = *(const LAS f32x4*)(CWL + k * 128 + cgp * 8 + 4);
;                 if (k < 4) { cw2[k][0] = (f32x2){a[0], a[1]}; cw2[k][1] = (f32x2){a[2], a[3]}; cw2[k][2] = (f32x2){c2[0], c2[1]}; cw2[k][3] = (f32x2){c2[2], c2[3]}; }
;                 else { cb2[0] = (f32x2){a[0], a[1]}; cb2[1] = (f32x2){a[2], a[3]}; cb2[2] = (f32x2){c2[0], c2[1]}; cb2[3] = (f32x2){c2[2], c2[3]}; } }
	v_mul_f32_e32 v0, 0xbfb8aa3b, v14
	s_waitcnt vmcnt(11)
	v_mul_f32_e32 v16, 0xbfb8aa3b, v9
	v_mad_u32_u24 v48, v15, s89, v2
	v_mul_lo_u32 v54, v38, s30
	v_mul_lo_u32 v55, v40, s30
	v_mul_lo_u32 v56, v42, s30
	v_ashrrev_i32_e32 v138, 2, v13
	v_mul_lo_u32 v130, v129, s89
	v_mul_lo_u32 v131, v129, s30
	v_mul_lo_u32 v133, v132, s89
	v_mul_lo_u32 v134, v132, s30
	v_mul_lo_u32 v146, v135, s89
	v_mul_lo_u32 v147, v135, s30
	v_mul_lo_u32 v148, v142, s89
	v_mul_lo_u32 v149, v142, s30
	v_mul_lo_u32 v162, v143, s89
	v_mul_lo_u32 v163, v143, s30
	v_mul_lo_u32 v63, v63, s87
	v_mul_lo_u32 v129, v129, s87
	v_mul_lo_u32 v132, v132, s87
	v_mul_lo_u32 v135, v135, s87
	v_mul_lo_u32 v219, v142, s87
	v_mul_lo_u32 v220, v143, s87
	v_lshl_add_u64 v[36:37], v[36:37], 0, v[64:65]
	v_lshl_add_u64 v[150:151], s[42:43], 0, v[32:33]
	v_mov_b32_e32 v64, v65
	v_add_u32_e32 v32, 0, v35
	v_add_u32_e32 v180, v49, v112
	v_add_u32_e32 v181, v50, v113
	v_add_u32_e32 v182, v49, v114
	v_add_u32_e32 v183, v50, v115
	v_add_u32_e32 v184, v49, v116
	v_add_u32_e32 v185, v50, v117
	v_add_u32_e32 v186, v49, v118
	v_add_u32_e32 v187, v50, v119
	v_add_u32_e32 v188, v49, v121
	v_add_u32_e32 v189, v50, v122
	v_add_u32_e32 v190, v49, v124
	v_add_u32_e32 v191, v50, v125
	v_add_u32_e32 v192, v49, v127
	v_add_u32_e32 v213, v51, v120
	v_add_u32_e32 v214, v51, v123
	v_add_u32_e32 v215, v51, v126
	v_mov_b64_e32 v[114:115], v[66:67]
	v_mov_b64_e32 v[118:119], v[66:67]
	v_mov_b64_e32 v[122:123], v[66:67]
	v_mov_b64_e32 v[126:127], v[66:67]
	s_mov_b32 s78, 0
	v_mov_b32_e32 v156, 0xff800000
	v_mul_f32_e32 v159, 0xc138aa3b, v6
	v_cmp_eq_u32_e32 vcc, 0, v18
	v_mul_lo_u32 v164, v140, s87
	v_ashrrev_i32_e32 v141, 31, v140
	v_mul_lo_u32 v152, v138, s87
	v_ashrrev_i32_e32 v139, 31, v138
	v_mov_b32_e32 v1, v0
	v_mov_b32_e32 v2, v0
	v_mov_b32_e32 v3, v0
	v_mov_b32_e32 v4, v0
	v_mov_b32_e32 v5, v0
	v_mov_b32_e32 v6, v0
	v_mov_b32_e32 v7, v0
	v_mov_b32_e32 v8, v0
	v_mov_b32_e32 v9, v0
	v_mov_b32_e32 v10, v0
	v_mov_b32_e32 v11, v0
	v_mov_b32_e32 v12, v0
	v_mov_b32_e32 v13, v0
	v_mov_b32_e32 v14, v0
	v_mov_b32_e32 v15, v0
	v_mov_b32_e32 v17, v16
	v_mov_b32_e32 v18, v16
	v_mov_b32_e32 v19, v16
	v_mov_b32_e32 v20, v16
	v_mov_b32_e32 v21, v16
	v_mov_b32_e32 v22, v16
	v_mov_b32_e32 v23, v16
	v_mov_b32_e32 v24, v16
	v_mov_b32_e32 v25, v16
	v_mov_b32_e32 v26, v16
	v_mov_b32_e32 v27, v16
	v_mov_b32_e32 v28, v16
	v_mov_b32_e32 v29, v16
	v_mov_b32_e32 v30, v16
	v_mov_b32_e32 v31, v16
	v_lshl_add_u64 v[142:143], s[42:43], 0, v[36:37]
	s_movk_i32 s28, 0x100
	v_mov_b32_e32 v222, 0
	s_mov_b64 s[44:45], 0
	s_movk_i32 s25, 0x700
	v_add_u32_e32 v165, 0x15c00, v32
	v_add_u32_e32 v166, v44, v52
	v_add_u32_e32 v168, v45, v53
	v_add_u32_e32 v169, v45, v54
	v_add_u32_e32 v170, v45, v55
	v_add_u32_e32 v171, v45, v56
	v_add_u32_e32 v172, v47, v46
	v_add_u32_e32 v173, v48, v46
	v_add_u32_e32 v174, v49, v57
	v_add_u32_e32 v175, v50, v58
	v_add_u32_e32 v176, v49, v59
	v_add_u32_e32 v177, v50, v60
	v_add_u32_e32 v178, v49, v61
	v_add_u32_e32 v179, v50, v62
	v_add_u32_e32 v193, v50, v128
	v_add_u32_e32 v194, v49, v130
	v_add_u32_e32 v195, v50, v131
	v_add_u32_e32 v196, v49, v133
	v_add_u32_e32 v197, v50, v134
	v_add_u32_e32 v198, v49, v146
	v_add_u32_e32 v199, v50, v147
	v_add_u32_e32 v200, v49, v148
	v_add_u32_e32 v201, v50, v149
	v_add_u32_e32 v202, v49, v162
	v_add_u32_e32 v203, v50, v163
	v_add_u32_e32 v204, v49, v204
	v_add_u32_e32 v205, v50, v205
	v_add_u32_e32 v206, v51, v206
	v_add_u32_e32 v207, v51, v207
	v_add_u32_e32 v208, v51, v208
	v_add_u32_e32 v209, v51, v63
	v_add_u32_e32 v210, v51, v210
	v_add_u32_e32 v211, v51, v211
	v_add_u32_e32 v212, v51, v212
	v_add_u32_e32 v216, v51, v129
	v_add_u32_e32 v217, v51, v132
	v_add_u32_e32 v218, v51, v135
	v_add_u32_e32 v219, v51, v219
	v_add_u32_e32 v220, v51, v220
	v_add_u32_e32 v221, v51, v221
	v_mov_b64_e32 v[112:113], v[64:65]
	v_mov_b64_e32 v[116:117], v[64:65]
	v_mov_b64_e32 v[120:121], v[64:65]
	v_mov_b64_e32 v[124:125], v[64:65]
	s_mov_b32 s46, 0
	s_mov_b32 s29, 0
	v_lshrrev_b32_e32 v32, 8, v167
	v_mul_u32_u24_e32 v33, 0x3600, v32
	v_add_u32_e32 v168, v168, v33
	v_add_u32_e32 v169, v169, v33
	v_add_u32_e32 v170, v170, v33
	v_add_u32_e32 v171, v171, v33
	v_add_u32_e32 v169, 0xffffee00, v169
	v_add_u32_e32 v170, 0xffffdc00, v170
	v_add_u32_e32 v171, 0xffffca00, v171
	v_mul_u32_u24_e32 v66, 0x60000, v32
	v_mov_b32_e32 v67, 0
	v_lshl_add_u64 v[142:143], v[66:67], 0, v[142:143]
	v_lshl_add_u64 v[252:253], v[66:67], 0, v[252:253]
	v_lshl_add_u64 v[154:155], v[66:67], 0, v[154:155]
	v_lshl_add_u64 v[150:151], v[66:67], 0, v[150:151]
	s_mov_b32 s19, -1
	s_mov_b32 s18, 0xfffe0000
	v_lshl_add_u64 v[252:253], v[252:253], 0, s[18:19]
	s_mov_b32 s18, 0xfffc0000
	v_lshl_add_u64 v[154:155], v[154:155], 0, s[18:19]
	s_mov_b32 s18, 0xfffa0000
	v_lshl_add_u64 v[150:151], v[150:151], 0, s[18:19]
	v_mul_u32_u24_e32 v33, 0x1400, v32
	v_add_u32_e32 v164, v164, v33
	v_add_u32_e32 v152, v152, v33
	v_add_u32_e32 v152, 0xffffec00, v152
	v_lshlrev_b32_e32 v33, 6, v32
	v_add_u32_e32 v140, v140, v33
	v_add_u32_e32 v138, v138, v33
	v_add_u32_e32 v138, 0xffffffc0, v138
	v_lshrrev_b32_e32 v33, 6, v167
	s_nop 1
	v_readfirstlane_b32 s18, v33
	s_lshl_b32 s19, s18, 6
	s_sub_i32 s19, s19, 0xe0
	s_mul_i32 s20, s19, 0x110
	v_add_u32_e32 v172, s20, v172
	v_add_u32_e32 v174, s20, v174
	v_add_u32_e32 v176, s20, v176
	v_add_u32_e32 v178, s20, v178
	v_add_u32_e32 v180, s20, v180
	v_add_u32_e32 v182, s20, v182
	v_add_u32_e32 v184, s20, v184
	v_add_u32_e32 v186, s20, v186
	v_add_u32_e32 v188, s20, v188
	v_add_u32_e32 v190, s20, v190
	v_add_u32_e32 v192, s20, v192
	v_add_u32_e32 v194, s20, v194
	v_add_u32_e32 v196, s20, v196
; #define LAS __attribute__((address_space(3)))
; __device__ __forceinline__ float bf_lo(unsigned u) { return __uint_as_float(u << 16); }
; __device__ __forceinline__ float bf_hi(unsigned u) { return __uint_as_float(u & 0xffff0000u); }
; template <int dir>
; __device__ __forceinline__ void lru_pass(LAS unsigned char* lds, const Params& P, int b, int h, int q, bool dry) {
;     ...
;         for (int sc = 0; sc < 9; ++sc) {
;             const bool isctx = (sc == 0);
;             const int t0 = cur.t0;
; #pragma unroll
;             for (int j = 0; j < 11; ++j) { if (j != 0 && j < 9) continue;
;                 const int t = t0 + tr * 8 - 1 + j; if (t < 0 || t >= cur.L) rows[j] = (u32x4){0u, 0u, 0u, 0u}; }
;             f32x2 cw2[4][4], cb2[4];
; #pragma unroll
;             for (int k = 0; k < 5; ++k) { const f32x4 a = *(const LAS f32x4*)(CWL + k * 128 + cgp * 8), c2 = *(const LAS f32x4*)(CWL + k * 128 + cgp * 8 + 4);
;                 if (k < 4) { cw2[k][0] = (f32x2){a[0], a[1]}; cw2[k][1] = (f32x2){a[2], a[3]}; cw2[k][2] = (f32x2){c2[0], c2[1]}; cw2[k][3] = (f32x2){c2[2], c2[3]}; }
;                 else { cb2[0] = (f32x2){a[0], a[1]}; cb2[1] = (f32x2){a[2], a[3]}; cb2[2] = (f32x2){c2[0], c2[1]}; cb2[3] = (f32x2){c2[2], c2[3]}; } }
; #pragma unroll
;             for (int j = 0; j < 8; ++j) {
;                 f32x2 o0 = cb2[0], o1 = cb2[1], o2 = cb2[2], o3 = cb2[3];
; #pragma unroll
;                 for (int k = 0; k < 4; ++k) { const u32x4 rr = rows[j + k];
;                     o0 = cw2[k][0] * (f32x2){bf_lo(rr.x), bf_hi(rr.x)} + o0; o1 = cw2[k][1] * (f32x2){bf_lo(rr.y), bf_hi(rr.y)} + o1;
;                     o2 = cw2[k][2] * (f32x2){bf_lo(rr.z), bf_hi(rr.z)} + o2; o3 = cw2[k][3] * (f32x2){bf_lo(rr.w), bf_hi(rr.w)} + o3; }
	v_add_u32_e32 v198, s20, v198
	v_add_u32_e32 v200, s20, v200
	v_add_u32_e32 v202, s20, v202
	v_add_u32_e32 v204, s20, v204
	s_mul_i32 s20, s19, 0x90
	v_add_u32_e32 v175, s20, v175
	v_add_u32_e32 v177, s20, v177
	v_add_u32_e32 v179, s20, v179
	v_add_u32_e32 v181, s20, v181
	v_add_u32_e32 v183, s20, v183
	v_add_u32_e32 v185, s20, v185
	v_add_u32_e32 v187, s20, v187
	v_add_u32_e32 v189, s20, v189
	v_add_u32_e32 v191, s20, v191
	v_add_u32_e32 v193, s20, v193
	v_add_u32_e32 v195, s20, v195
	v_add_u32_e32 v197, s20, v197
	v_add_u32_e32 v199, s20, v199
	v_add_u32_e32 v201, s20, v201
	v_add_u32_e32 v203, s20, v203
	v_add_u32_e32 v205, s20, v205
	s_mul_i32 s20, s19, 0x50
	v_add_u32_e32 v206, s20, v206
	v_add_u32_e32 v207, s20, v207
	v_add_u32_e32 v208, s20, v208
	v_add_u32_e32 v209, s20, v209
	v_add_u32_e32 v210, s20, v210
	v_add_u32_e32 v211, s20, v211
	v_add_u32_e32 v212, s20, v212
	v_add_u32_e32 v213, s20, v213
	v_add_u32_e32 v214, s20, v214
	v_add_u32_e32 v215, s20, v215
	v_add_u32_e32 v216, s20, v216
	v_add_u32_e32 v217, s20, v217
	v_add_u32_e32 v218, s20, v218
	v_add_u32_e32 v219, s20, v219
	v_add_u32_e32 v220, s20, v220
	v_add_u32_e32 v221, s20, v221
	s_lshl_b32 s20, s18, 1
	s_sub_i32 s20, 7, s20
	s_lshl_b32 s20, s20, 8
	v_add_u32_e32 v254, s20, v254
	s_sub_i32 s18, 7, s18
	s_lshr_b32 s101, s18, 2
	s_or_b32 s19, s18, 4
	s_cmp_eq_u32 s19, 7
	s_cselect_b64 s[0:1], -1, 0
	s_cmp_eq_u32 s19, 6
	s_cselect_b64 s[16:17], -1, 0
	s_cmp_eq_u32 s19, 5
	s_cselect_b64 s[4:5], -1, 0
	s_cmp_eq_u32 s19, 4
	s_cselect_b64 s[8:9], -1, 0
	s_cmp_eq_u32 s19, 3
	s_cselect_b64 s[10:11], -1, 0
	s_cmp_eq_u32 s19, 2
	s_cselect_b64 s[12:13], -1, 0
	s_cmp_eq_u32 s19, 1
	s_cselect_b64 s[14:15], -1, 0
	s_mov_b32 s98, 0
	s_cmp_eq_u32 s101, 0
	s_cselect_b32 s99, 0x14400, 0
	s_cselect_b32 s100, 0, 0x400
	v_add_u32_e32 v33, 0x14000, v254
	v_mov_b32_e32 v66, 1.0
	v_mov_b32_e32 v67, 0
	ds_write2_b32 v33, v66, v67 offset1:32
	s_cmp_eq_u32 s101, 0
	s_cbranch_scc1 .Lpp_b_nox
	s_waitcnt lgkmcnt(0)
	s_barrier
.Lpp_b_nox:
.LBB0_306:
	v_add_u32_e32 v32, s29, v160
	v_cmp_lt_i32_e64 s[18:19], -1, v32
	v_cmp_gt_i32_e64 s[20:21], s28, v32
	s_and_b64 s[18:19], s[18:19], s[20:21]
	v_add_u32_e32 v33, 9, v32
	s_waitcnt vmcnt(10)
	v_cndmask_b32_e64 v71, 0, v71, s[18:19]
	v_cndmask_b32_e64 v70, 0, v70, s[18:19]
	v_cndmask_b32_e64 v69, 0, v69, s[18:19]
	v_cndmask_b32_e64 v68, 0, v68, s[18:19]
	v_cmp_lt_i32_e64 s[18:19], -10, v32
	v_cmp_gt_i32_e64 s[20:21], s28, v33
	s_and_b64 s[18:19], s[18:19], s[20:21]
	v_add_u32_e32 v33, 10, v32
	s_waitcnt vmcnt(1)
	v_cndmask_b32_e64 v107, 0, v107, s[18:19]
	v_cndmask_b32_e64 v106, 0, v106, s[18:19]
	v_cndmask_b32_e64 v105, 0, v105, s[18:19]
	v_cndmask_b32_e64 v104, 0, v104, s[18:19]
	v_cmp_lt_i32_e64 s[18:19], -11, v32
	v_cmp_gt_i32_e64 s[20:21], s28, v33
	ds_read_b128 v[60:63], v165
	ds_read_b128 v[52:55], v165 offset:256
	ds_read_b128 v[44:47], v165 offset:768
	ds_read_b128 v[56:59], v165 offset:512
	ds_read_b128 v[40:43], v165 offset:1280
	ds_read_b128 v[48:51], v165 offset:1024
	ds_read_b128 v[128:131], v165 offset:2304
	ds_read_b128 v[132:135], v165 offset:2048
	ds_read_b128 v[32:35], v165 offset:1792
	ds_read_b128 v[36:39], v165 offset:1536
	v_lshlrev_b32_e32 v66, 16, v68
	v_and_b32_e32 v67, 0xffff0000, v68
	v_lshlrev_b32_e32 v148, 16, v70
	v_and_b32_e32 v149, 0xffff0000, v70
	s_waitcnt lgkmcnt(2)
	v_pk_fma_f32 v[66:67], v[60:61], v[66:67], v[132:133]
	v_lshlrev_b32_e32 v146, 16, v69
	v_and_b32_e32 v147, 0xffff0000, v69
	v_pk_fma_f32 v[148:149], v[52:53], v[148:149], v[128:129]
	v_lshlrev_b32_e32 v224, 16, v71
	v_and_b32_e32 v225, 0xffff0000, v71
	v_lshlrev_b32_e32 v228, 16, v72
	v_and_b32_e32 v229, 0xffff0000, v72
	v_lshlrev_b32_e32 v232, 16, v74
	v_and_b32_e32 v233, 0xffff0000, v74
	v_pk_fma_f32 v[146:147], v[62:63], v[146:147], v[134:135]
	v_pk_fma_f32 v[224:225], v[54:55], v[224:225], v[130:131]
	v_pk_fma_f32 v[66:67], v[56:57], v[228:229], v[66:67]
	v_lshlrev_b32_e32 v230, 16, v73
	v_and_b32_e32 v231, 0xffff0000, v73
	v_pk_fma_f32 v[148:149], v[44:45], v[232:233], v[148:149]
	v_lshlrev_b32_e32 v234, 16, v75
	v_and_b32_e32 v235, 0xffff0000, v75
	v_lshlrev_b32_e32 v236, 16, v76
	v_and_b32_e32 v237, 0xffff0000, v76
	v_lshlrev_b32_e32 v240, 16, v78
	v_and_b32_e32 v241, 0xffff0000, v78
	v_pk_fma_f32 v[146:147], v[58:59], v[230:231], v[146:147]
	v_pk_fma_f32 v[224:225], v[46:47], v[234:235], v[224:225]
	v_pk_fma_f32 v[66:67], v[48:49], v[236:237], v[66:67]
	v_lshlrev_b32_e32 v238, 16, v77
	v_and_b32_e32 v239, 0xffff0000, v77
	v_pk_fma_f32 v[148:149], v[40:41], v[240:241], v[148:149]
	v_lshlrev_b32_e32 v242, 16, v79
	v_and_b32_e32 v243, 0xffff0000, v79
	v_lshlrev_b32_e32 v244, 16, v80
	v_and_b32_e32 v245, 0xffff0000, v80
	v_lshlrev_b32_e32 v248, 16, v82
	v_and_b32_e32 v249, 0xffff0000, v82
	v_pk_fma_f32 v[146:147], v[50:51], v[238:239], v[146:147]
	v_pk_fma_f32 v[224:225], v[42:43], v[242:243], v[224:225]
	s_waitcnt lgkmcnt(0)
; #define LAS __attribute__((address_space(3)))
; __device__ __forceinline__ unsigned cvt_pk_bf16(float lo, float hi) { unsigned r; asm volatile("v_cvt_pk_bf16_f32 %0, %1, %2" : "=v"(r) : "v"(lo), "v"(hi)); return r; }
; __device__ __forceinline__ float bf_lo(unsigned u) { return __uint_as_float(u << 16); }
; __device__ __forceinline__ float bf_hi(unsigned u) { return __uint_as_float(u & 0xffff0000u); }
; template <int dir>
; __device__ __forceinline__ void lru_pass(LAS unsigned char* lds, const Params& P, int b, int h, int q, bool dry) {
;     ...
;             for (int j = 0; j < 8; ++j) {
;                 f32x2 o0 = cb2[0], o1 = cb2[1], o2 = cb2[2], o3 = cb2[3];
; #pragma unroll
;                 for (int k = 0; k < 4; ++k) { const u32x4 rr = rows[j + k];
;                     o0 = cw2[k][0] * (f32x2){bf_lo(rr.x), bf_hi(rr.x)} + o0; o1 = cw2[k][1] * (f32x2){bf_lo(rr.y), bf_hi(rr.y)} + o1;
;                     o2 = cw2[k][2] * (f32x2){bf_lo(rr.z), bf_hi(rr.z)} + o2; o3 = cw2[k][3] * (f32x2){bf_lo(rr.w), bf_hi(rr.w)} + o3; }
;                 u32x4 w; w.x = cvt_pk_bf16(o0[0], o0[1]); w.y = cvt_pk_bf16(o1[0], o1[1]); w.z = cvt_pk_bf16(o2[0], o2[1]); w.w = cvt_pk_bf16(o3[0], o3[1]);
;                 *(LAS u32x4*)(XC + (tr * 8 + j) * XC_PITCH + cgp * 16) = w;
;             }
	v_pk_fma_f32 v[66:67], v[36:37], v[244:245], v[66:67]
	v_lshlrev_b32_e32 v246, 16, v81
	v_and_b32_e32 v247, 0xffff0000, v81
	v_pk_fma_f32 v[148:149], v[32:33], v[248:249], v[148:149]
	v_lshlrev_b32_e32 v250, 16, v83
	v_and_b32_e32 v251, 0xffff0000, v83
	v_pk_fma_f32 v[146:147], v[38:39], v[246:247], v[146:147]
	v_pk_fma_f32 v[162:163], v[34:35], v[250:251], v[224:225]
	v_cvt_pk_bf16_f32 v224, v66, v67
	v_cvt_pk_bf16_f32 v225, v146, v147
	v_cvt_pk_bf16_f32 v226, v148, v149
	v_pk_fma_f32 v[66:67], v[60:61], v[228:229], v[132:133]
	v_pk_fma_f32 v[148:149], v[52:53], v[232:233], v[128:129]
	v_pk_fma_f32 v[146:147], v[62:63], v[230:231], v[134:135]
	v_pk_fma_f32 v[66:67], v[56:57], v[236:237], v[66:67]
	v_pk_fma_f32 v[148:149], v[44:45], v[240:241], v[148:149]
	v_pk_fma_f32 v[146:147], v[58:59], v[238:239], v[146:147]
	v_pk_fma_f32 v[66:67], v[48:49], v[244:245], v[66:67]
	v_pk_fma_f32 v[148:149], v[40:41], v[248:249], v[148:149]
	v_lshlrev_b32_e32 v228, 16, v84
	v_and_b32_e32 v229, 0xffff0000, v84
	v_lshlrev_b32_e32 v232, 16, v86
	v_and_b32_e32 v233, 0xffff0000, v86
	v_cvt_pk_bf16_f32 v227, v162, v163
	v_pk_fma_f32 v[162:163], v[54:55], v[234:235], v[130:131]
	v_pk_fma_f32 v[146:147], v[50:51], v[246:247], v[146:147]
	v_pk_fma_f32 v[66:67], v[36:37], v[228:229], v[66:67]
	v_lshlrev_b32_e32 v230, 16, v85
	v_and_b32_e32 v231, 0xffff0000, v85
	v_pk_fma_f32 v[148:149], v[32:33], v[232:233], v[148:149]
	ds_write_b128 v166, v[224:227]
	v_pk_fma_f32 v[162:163], v[46:47], v[242:243], v[162:163]
	v_pk_fma_f32 v[146:147], v[38:39], v[230:231], v[146:147]
	v_cvt_pk_bf16_f32 v224, v66, v67
	v_pk_fma_f32 v[66:67], v[60:61], v[236:237], v[132:133]
	v_cvt_pk_bf16_f32 v225, v146, v147
	v_cvt_pk_bf16_f32 v226, v148, v149
	v_pk_fma_f32 v[148:149], v[52:53], v[240:241], v[128:129]
	v_pk_fma_f32 v[162:163], v[42:43], v[250:251], v[162:163]
	v_lshlrev_b32_e32 v234, 16, v87
	v_and_b32_e32 v235, 0xffff0000, v87
	v_pk_fma_f32 v[146:147], v[62:63], v[238:239], v[134:135]
	v_pk_fma_f32 v[66:67], v[56:57], v[244:245], v[66:67]
	v_pk_fma_f32 v[148:149], v[44:45], v[248:249], v[148:149]
	v_pk_fma_f32 v[162:163], v[34:35], v[234:235], v[162:163]
	v_pk_fma_f32 v[146:147], v[58:59], v[246:247], v[146:147]
	v_pk_fma_f32 v[66:67], v[48:49], v[228:229], v[66:67]
	v_pk_fma_f32 v[148:149], v[40:41], v[232:233], v[148:149]
	v_lshlrev_b32_e32 v236, 16, v88
	v_and_b32_e32 v237, 0xffff0000, v88
	v_lshlrev_b32_e32 v240, 16, v90
	v_and_b32_e32 v241, 0xffff0000, v90
	v_cvt_pk_bf16_f32 v227, v162, v163
	v_pk_fma_f32 v[162:163], v[54:55], v[242:243], v[130:131]
	v_pk_fma_f32 v[146:147], v[50:51], v[230:231], v[146:147]
	v_pk_fma_f32 v[66:67], v[36:37], v[236:237], v[66:67]
	v_lshlrev_b32_e32 v238, 16, v89
	v_and_b32_e32 v239, 0xffff0000, v89
	v_pk_fma_f32 v[148:149], v[32:33], v[240:241], v[148:149]
	ds_write_b128 v166, v[224:227] offset:272
	v_pk_fma_f32 v[162:163], v[46:47], v[250:251], v[162:163]
	v_pk_fma_f32 v[146:147], v[38:39], v[238:239], v[146:147]
	v_cvt_pk_bf16_f32 v224, v66, v67
	v_pk_fma_f32 v[66:67], v[60:61], v[244:245], v[132:133]
	v_cvt_pk_bf16_f32 v225, v146, v147
	v_cvt_pk_bf16_f32 v226, v148, v149
	v_pk_fma_f32 v[148:149], v[52:53], v[248:249], v[128:129]
	v_pk_fma_f32 v[162:163], v[42:43], v[234:235], v[162:163]
	v_lshlrev_b32_e32 v242, 16, v91
	v_and_b32_e32 v243, 0xffff0000, v91
	v_pk_fma_f32 v[146:147], v[62:63], v[246:247], v[134:135]
	v_pk_fma_f32 v[66:67], v[56:57], v[228:229], v[66:67]
	v_pk_fma_f32 v[148:149], v[44:45], v[232:233], v[148:149]
	v_pk_fma_f32 v[162:163], v[34:35], v[242:243], v[162:163]
	v_pk_fma_f32 v[146:147], v[58:59], v[230:231], v[146:147]
	v_pk_fma_f32 v[66:67], v[48:49], v[236:237], v[66:67]
	v_pk_fma_f32 v[148:149], v[40:41], v[240:241], v[148:149]
	v_lshlrev_b32_e32 v244, 16, v92
	v_and_b32_e32 v245, 0xffff0000, v92
	v_lshlrev_b32_e32 v248, 16, v94
	v_and_b32_e32 v249, 0xffff0000, v94
	v_cvt_pk_bf16_f32 v227, v162, v163
	v_pk_fma_f32 v[162:163], v[54:55], v[250:251], v[130:131]
	v_pk_fma_f32 v[146:147], v[50:51], v[238:239], v[146:147]
	v_pk_fma_f32 v[66:67], v[36:37], v[244:245], v[66:67]
	v_lshlrev_b32_e32 v246, 16, v93
	v_and_b32_e32 v247, 0xffff0000, v93
	v_pk_fma_f32 v[148:149], v[32:33], v[248:249], v[148:149]
	ds_write_b128 v166, v[224:227] offset:544
	v_pk_fma_f32 v[162:163], v[46:47], v[234:235], v[162:163]
	v_pk_fma_f32 v[146:147], v[38:39], v[246:247], v[146:147]
	v_cvt_pk_bf16_f32 v224, v66, v67
	v_pk_fma_f32 v[66:67], v[60:61], v[228:229], v[132:133]
	v_cvt_pk_bf16_f32 v225, v146, v147
	v_cvt_pk_bf16_f32 v226, v148, v149
	v_pk_fma_f32 v[148:149], v[52:53], v[232:233], v[128:129]
	v_pk_fma_f32 v[162:163], v[42:43], v[242:243], v[162:163]
	v_lshlrev_b32_e32 v250, 16, v95
	v_and_b32_e32 v251, 0xffff0000, v95
	v_pk_fma_f32 v[146:147], v[62:63], v[230:231], v[134:135]
	v_pk_fma_f32 v[66:67], v[56:57], v[236:237], v[66:67]
	v_pk_fma_f32 v[148:149], v[44:45], v[240:241], v[148:149]
	v_pk_fma_f32 v[162:163], v[34:35], v[250:251], v[162:163]
	v_pk_fma_f32 v[146:147], v[58:59], v[238:239], v[146:147]
	v_pk_fma_f32 v[66:67], v[48:49], v[244:245], v[66:67]
	v_pk_fma_f32 v[148:149], v[40:41], v[248:249], v[148:149]
	v_lshlrev_b32_e32 v228, 16, v96
	v_and_b32_e32 v229, 0xffff0000, v96
	v_lshlrev_b32_e32 v232, 16, v98
	v_and_b32_e32 v233, 0xffff0000, v98
	v_cvt_pk_bf16_f32 v227, v162, v163
	v_pk_fma_f32 v[162:163], v[54:55], v[234:235], v[130:131]
	v_pk_fma_f32 v[146:147], v[50:51], v[246:247], v[146:147]
	v_pk_fma_f32 v[66:67], v[36:37], v[228:229], v[66:67]
	v_lshlrev_b32_e32 v230, 16, v97
	v_and_b32_e32 v231, 0xffff0000, v97
	v_pk_fma_f32 v[148:149], v[32:33], v[232:233], v[148:149]
	ds_write_b128 v166, v[224:227] offset:816
; #define LAS __attribute__((address_space(3)))
; __device__ __forceinline__ unsigned cvt_pk_bf16(float lo, float hi) { unsigned r; asm volatile("v_cvt_pk_bf16_f32 %0, %1, %2" : "=v"(r) : "v"(lo), "v"(hi)); return r; }
; __device__ __forceinline__ float bf_lo(unsigned u) { return __uint_as_float(u << 16); }
; __device__ __forceinline__ float bf_hi(unsigned u) { return __uint_as_float(u & 0xffff0000u); }
; template <int dir>
; __device__ __forceinline__ void lru_pass(LAS unsigned char* lds, const Params& P, int b, int h, int q, bool dry) {
;     ...
;             for (int j = 0; j < 8; ++j) {
;                 f32x2 o0 = cb2[0], o1 = cb2[1], o2 = cb2[2], o3 = cb2[3];
; #pragma unroll
;                 for (int k = 0; k < 4; ++k) { const u32x4 rr = rows[j + k];
;                     o0 = cw2[k][0] * (f32x2){bf_lo(rr.x), bf_hi(rr.x)} + o0; o1 = cw2[k][1] * (f32x2){bf_lo(rr.y), bf_hi(rr.y)} + o1;
;                     o2 = cw2[k][2] * (f32x2){bf_lo(rr.z), bf_hi(rr.z)} + o2; o3 = cw2[k][3] * (f32x2){bf_lo(rr.w), bf_hi(rr.w)} + o3; }
;                 u32x4 w; w.x = cvt_pk_bf16(o0[0], o0[1]); w.y = cvt_pk_bf16(o1[0], o1[1]); w.z = cvt_pk_bf16(o2[0], o2[1]); w.w = cvt_pk_bf16(o3[0], o3[1]);
;                 *(LAS u32x4*)(XC + (tr * 8 + j) * XC_PITCH + cgp * 16) = w;
;             }
; #pragma unroll
;             for (int i = 0; i < NIN; ++i) { const int id = tid + i * NTHREADS;
;                 if (dir == 0) *(LAS u32x4*)(TIN + (id >> 2) * IO_NP + (id & 3) * 16) = inr[i];
;                 else *(LAS u32x4*)(TIN + (id >> 3) * IO_WP + (id & 7) * 16) = inr[i]; }
;             LruTile nxt = cur;
;             if (sc < 8) { nxt = lru_tile(Z, ZC, b, h, dir, sc + 1); lru_load_rows(rows, nxt, tr, cgp);
; #pragma unroll
;                 for (int i = 0; i < NIN; ++i) { const int id = tid + i * NTHREADS;
;                     if (dir == 0) inr[i] = *(const u32x4*)(Zg + (size_t)(nxt.t0 + (id >> 2)) * 128 + (id & 3) * 8);
;                     else inr[i] = *(const u32x4*)(Hg + (size_t)(nxt.t0 + (id >> 3)) * DM + (id & 7) * 4); } }
	v_pk_fma_f32 v[162:163], v[46:47], v[242:243], v[162:163]
	v_pk_fma_f32 v[146:147], v[38:39], v[230:231], v[146:147]
	v_cvt_pk_bf16_f32 v224, v66, v67
	v_pk_fma_f32 v[66:67], v[60:61], v[236:237], v[132:133]
	v_cvt_pk_bf16_f32 v225, v146, v147
	v_cvt_pk_bf16_f32 v226, v148, v149
	v_pk_fma_f32 v[148:149], v[52:53], v[240:241], v[128:129]
	v_pk_fma_f32 v[162:163], v[42:43], v[250:251], v[162:163]
	v_lshlrev_b32_e32 v234, 16, v99
	v_and_b32_e32 v235, 0xffff0000, v99
	v_pk_fma_f32 v[146:147], v[62:63], v[238:239], v[134:135]
	v_pk_fma_f32 v[66:67], v[56:57], v[244:245], v[66:67]
	v_pk_fma_f32 v[148:149], v[44:45], v[248:249], v[148:149]
	v_pk_fma_f32 v[162:163], v[34:35], v[234:235], v[162:163]
	v_pk_fma_f32 v[146:147], v[58:59], v[246:247], v[146:147]
	v_pk_fma_f32 v[66:67], v[48:49], v[228:229], v[66:67]
	v_pk_fma_f32 v[148:149], v[40:41], v[232:233], v[148:149]
	v_lshlrev_b32_e32 v236, 16, v100
	v_and_b32_e32 v237, 0xffff0000, v100
	v_lshlrev_b32_e32 v240, 16, v102
	v_and_b32_e32 v241, 0xffff0000, v102
	v_cvt_pk_bf16_f32 v227, v162, v163
	v_pk_fma_f32 v[162:163], v[54:55], v[242:243], v[130:131]
	v_pk_fma_f32 v[146:147], v[50:51], v[230:231], v[146:147]
	v_pk_fma_f32 v[66:67], v[36:37], v[236:237], v[66:67]
	v_lshlrev_b32_e32 v238, 16, v101
	v_and_b32_e32 v239, 0xffff0000, v101
	v_pk_fma_f32 v[148:149], v[32:33], v[240:241], v[148:149]
	s_and_b64 s[18:19], s[18:19], s[20:21]
	ds_write_b128 v166, v[224:227] offset:1088
	v_pk_fma_f32 v[162:163], v[46:47], v[250:251], v[162:163]
	v_pk_fma_f32 v[146:147], v[38:39], v[238:239], v[146:147]
	v_cvt_pk_bf16_f32 v224, v66, v67
	v_pk_fma_f32 v[66:67], v[60:61], v[244:245], v[132:133]
	v_cvt_pk_bf16_f32 v225, v146, v147
	v_cvt_pk_bf16_f32 v226, v148, v149
	v_pk_fma_f32 v[148:149], v[52:53], v[248:249], v[128:129]
	v_pk_fma_f32 v[60:61], v[60:61], v[228:229], v[132:133]
	v_pk_fma_f32 v[52:53], v[52:53], v[232:233], v[128:129]
	s_waitcnt vmcnt(0)
	v_cndmask_b32_e64 v108, 0, v108, s[18:19]
	v_pk_fma_f32 v[162:163], v[42:43], v[234:235], v[162:163]
	v_lshlrev_b32_e32 v242, 16, v103
	v_and_b32_e32 v243, 0xffff0000, v103
	v_pk_fma_f32 v[146:147], v[62:63], v[246:247], v[134:135]
	v_pk_fma_f32 v[66:67], v[56:57], v[228:229], v[66:67]
	v_pk_fma_f32 v[148:149], v[44:45], v[232:233], v[148:149]
	v_lshlrev_b32_e32 v244, 16, v104
	v_and_b32_e32 v245, 0xffff0000, v104
	v_lshlrev_b32_e32 v248, 16, v106
	v_and_b32_e32 v249, 0xffff0000, v106
	v_pk_fma_f32 v[62:63], v[62:63], v[230:231], v[134:135]
	v_pk_fma_f32 v[56:57], v[56:57], v[236:237], v[60:61]
	v_pk_fma_f32 v[44:45], v[44:45], v[240:241], v[52:53]
	v_cndmask_b32_e64 v109, 0, v109, s[18:19]
	v_pk_fma_f32 v[162:163], v[34:35], v[242:243], v[162:163]
	v_pk_fma_f32 v[146:147], v[58:59], v[230:231], v[146:147]
	v_pk_fma_f32 v[66:67], v[48:49], v[236:237], v[66:67]
	v_pk_fma_f32 v[148:149], v[40:41], v[240:241], v[148:149]
	v_lshlrev_b32_e32 v246, 16, v105
	v_and_b32_e32 v247, 0xffff0000, v105
	v_pk_fma_f32 v[58:59], v[58:59], v[238:239], v[62:63]
	v_pk_fma_f32 v[48:49], v[48:49], v[244:245], v[56:57]
	v_pk_fma_f32 v[40:41], v[40:41], v[248:249], v[44:45]
	v_lshlrev_b32_e32 v44, 16, v108
	v_and_b32_e32 v45, 0xffff0000, v108
	v_cndmask_b32_e64 v110, 0, v110, s[18:19]
	v_cvt_pk_bf16_f32 v227, v162, v163
	v_pk_fma_f32 v[162:163], v[54:55], v[250:251], v[130:131]
	v_pk_fma_f32 v[146:147], v[50:51], v[238:239], v[146:147]
	v_pk_fma_f32 v[66:67], v[36:37], v[244:245], v[66:67]
	v_pk_fma_f32 v[54:55], v[54:55], v[234:235], v[130:131]
	v_pk_fma_f32 v[50:51], v[50:51], v[246:247], v[58:59]
	v_pk_fma_f32 v[36:37], v[36:37], v[44:45], v[48:49]
	v_lshlrev_b32_e32 v44, 16, v109
	v_and_b32_e32 v45, 0xffff0000, v109
	v_cndmask_b32_e64 v111, 0, v111, s[18:19]
	v_pk_fma_f32 v[162:163], v[46:47], v[234:235], v[162:163]
	v_pk_fma_f32 v[146:147], v[38:39], v[246:247], v[146:147]
	v_lshlrev_b32_e32 v250, 16, v107
	v_and_b32_e32 v251, 0xffff0000, v107
	v_pk_fma_f32 v[46:47], v[46:47], v[242:243], v[54:55]
	v_pk_fma_f32 v[38:39], v[38:39], v[44:45], v[50:51]
	v_lshlrev_b32_e32 v44, 16, v110
	v_and_b32_e32 v45, 0xffff0000, v110
	v_pk_fma_f32 v[162:163], v[42:43], v[242:243], v[162:163]
	v_pk_fma_f32 v[148:149], v[32:33], v[248:249], v[148:149]
	v_pk_fma_f32 v[42:43], v[42:43], v[250:251], v[46:47]
	v_pk_fma_f32 v[40:41], v[32:33], v[44:45], v[40:41]
	v_lshlrev_b32_e32 v32, 16, v111
	v_and_b32_e32 v33, 0xffff0000, v111
	ds_write_b128 v166, v[224:227] offset:1360
	v_pk_fma_f32 v[162:163], v[34:35], v[250:251], v[162:163]
	v_cvt_pk_bf16_f32 v224, v66, v67
	v_cvt_pk_bf16_f32 v225, v146, v147
	v_cvt_pk_bf16_f32 v226, v148, v149
	v_pk_fma_f32 v[42:43], v[34:35], v[32:33], v[42:43]
	v_cvt_pk_bf16_f32 v227, v162, v163
	ds_write_b128 v166, v[224:227] offset:1632
	v_cvt_pk_bf16_f32 v32, v36, v37
	v_cvt_pk_bf16_f32 v33, v38, v39
	v_cvt_pk_bf16_f32 v34, v40, v41
	v_cvt_pk_bf16_f32 v35, v42, v43
	s_cmp_eq_u32 s44, 0xff800000
	ds_write_b128 v166, v[32:35] offset:1904
	ds_write_b128 v168, v[112:115]
	ds_write_b128 v169, v[116:119]
	ds_write_b128 v170, v[120:123]
	ds_write_b128 v171, v[124:127]
	s_cbranch_scc1 .LBB0_308
	global_load_dwordx4 v[68:71], v[144:145], off offset:-1280
	global_load_dwordx4 v[72:75], v[144:145], off offset:-1024
	global_load_dwordx4 v[76:79], v[144:145], off offset:-768
	global_load_dwordx4 v[80:83], v[144:145], off offset:-512
	global_load_dwordx4 v[84:87], v[144:145], off offset:-256
	global_load_dwordx4 v[88:91], v[144:145], off
	global_load_dwordx4 v[92:95], v[144:145], off offset:256
	global_load_dwordx4 v[96:99], v[144:145], off offset:512
	global_load_dwordx4 v[100:103], v[144:145], off offset:768
	global_load_dwordx4 v[104:107], v[144:145], off offset:1024
	global_load_dwordx4 v[108:111], v[144:145], off offset:1280
	v_lshl_add_u64 v[32:33], v[142:143], 0, s[44:45]
	v_lshl_add_u64 v[34:35], v[252:253], 0, s[44:45]
	global_load_dwordx4 v[112:115], v[32:33], off sc1
	global_load_dwordx4 v[116:119], v[34:35], off sc1
	v_lshl_add_u64 v[32:33], v[154:155], 0, s[44:45]
	v_lshl_add_u64 v[34:35], v[150:151], 0, s[44:45]
	global_load_dwordx4 v[120:123], v[32:33], off sc1
	global_load_dwordx4 v[124:127], v[34:35], off sc1
	s_movk_i32 s28, 0x800
	s_mov_b32 s20, s25
	s_branch .LBB0_309
